# moe_down gate scaling: 64 serial gate loads per tile replaced by 4 16-byte loads; sgu epilogue sgn/bias values loaded once
# speedup vs baseline: 1.1907x; 1.0211x over previous
; __device__ __forceinline__ void phase_mix_a(const Params& p, int l, bool last, unsigned char* smem) {
;     ...
;       gemm_tile<2, true>(p.Wsgu + (size_t)(l * 4 + h) * 16384, 128, nullptr, 128, p.PX + (size_t)row_base * 1024 + 256 + h * 64, 1024, 128, smem, epi, rsv);
.LBB0_602:
	s_or_b64 exec, exec, s[0:1]
	s_and_b32 s1, s9, 3
	s_or_b32 s34, s1, s18
	s_lshl_b32 s94, s34, 7
	v_lshl_add_u64 v[60:61], s[94:95], 2, v[6:7]
	s_waitcnt lgkmcnt(0)
	v_lshl_add_u64 v[2:3], s[4:5], 2, v[8:9]
	s_lshl_b32 s94, s1, 8
	v_mov_b64_e32 v[58:59], s[40:41]
	v_lshl_add_u64 v[62:63], v[2:3], 0, s[94:95]
	global_load_dwordx2 v[2:3], v[58:59], off offset:240
	global_load_dwordx2 v[4:5], v[58:59], off offset:288
	v_mov_b32_e32 v46, v187
	s_ashr_i32 s39, s38, 31
	v_ashrrev_i32_e32 v10, 31, v46
	v_lshrrev_b32_e32 v10, 29, v10
	v_add_u32_e32 v12, v46, v10
	v_ashrrev_i32_e32 v44, 3, v12
	s_lshl_b32 s94, s34, 15
	s_lshl_b64 s[34:35], s[38:39], 11
	v_ashrrev_i32_e32 v45, 31, v44
	v_and_b32_e32 v12, -8, v12
	v_lshlrev_b64 v[10:11], 11, v[44:45]
	v_sub_u32_e32 v45, v46, v12
	v_lshlrev_b32_e32 v42, 3, v45
	v_ashrrev_i32_e32 v43, 31, v42
	v_add_u32_e32 v12, 0x100, v46
	v_lshlrev_b32_e32 v0, 3, v46
	v_and_b32_e32 v20, 56, v0
	v_lshlrev_b32_e32 v0, 1, v20
	s_waitcnt lgkmcnt(0)
	s_barrier
	s_lshl_b32 s0, s1, 6
	v_lshlrev_b32_e32 v67, 2, v20
	v_lshrrev_b32_e32 v47, 4, v46
	v_bfe_u32 v106, v46, 1, 3
	v_bfe_u32 v64, v46, 6, 1
	v_ashrrev_i32_e32 v65, 7, v46
	v_bfe_u32 v66, v46, 4, 2
	s_add_i32 s9, s9, s3
	s_waitcnt vmcnt(0)
	v_lshl_add_u64 v[2:3], v[2:3], 0, s[94:95]
	v_lshl_add_u64 v[4:5], v[4:5], 0, s[34:35]
	s_lshl_b32 s94, s1, 7
	v_lshl_add_u64 v[8:9], v[4:5], 0, s[94:95]
	v_lshl_add_u64 v[10:11], v[8:9], 0, v[10:11]
	v_lshl_add_u64 v[34:35], v[42:43], 1, v[10:11]
	v_ashrrev_i32_e32 v10, 31, v12
	v_lshrrev_b32_e32 v10, 29, v10
	v_add_u32_e32 v13, v12, v10
	v_ashrrev_i32_e32 v40, 3, v13
	v_ashrrev_i32_e32 v41, 31, v40
	v_lshlrev_b64 v[10:11], 11, v[40:41]
	v_ashrrev_i32_e32 v4, 3, v46
	v_lshl_add_u64 v[8:9], v[8:9], 0, v[10:11]
	v_and_b32_e32 v10, -8, v13
	v_ashrrev_i32_e32 v5, 31, v4
	v_sub_u32_e32 v41, v12, v10
	v_lshl_add_u64 v[2:3], v[2:3], 0, v[0:1]
	v_lshlrev_b64 v[4:5], 8, v[4:5]
	v_lshlrev_b32_e32 v38, 3, v41
	v_lshl_add_u64 v[2:3], v[2:3], 0, v[4:5]
	v_ashrrev_i32_e32 v39, 31, v38
	v_lshl_add_u64 v[36:37], v[38:39], 1, v[8:9]
	v_add_co_u32_e32 v8, vcc, s70, v2
	global_load_dwordx4 v[22:25], v[2:3], off
	s_nop 0
	v_addc_co_u32_e32 v9, vcc, 0, v3, vcc
	global_load_dwordx4 v[26:29], v[8:9], off
	v_add_co_u32_e32 v8, vcc, s69, v2
	s_movk_i32 s1, 0x6000
	s_nop 0
	v_addc_co_u32_e32 v9, vcc, 0, v3, vcc
	global_load_dwordx4 v[30:33], v[8:9], off
	s_mov_b64 s[34:35], 0x2000
	v_add_co_u32_e32 v8, vcc, s1, v2
	v_lshl_add_u64 v[4:5], v[2:3], 0, s[34:35]
	v_lshl_add_u64 v[6:7], v[2:3], 0, s[62:63]
	v_addc_co_u32_e32 v9, vcc, 0, v3, vcc
	v_lshl_add_u64 v[18:19], v[2:3], 0, s[24:25]
	global_load_dwordx4 v[48:51], v[8:9], off
	global_load_dwordx4 v[14:17], v[2:3], off offset:128
	global_load_dwordx4 v[10:13], v[4:5], off offset:128
	s_nop 0
	global_load_dwordx4 v[6:9], v[6:7], off offset:128
	s_nop 0
	global_load_dwordx4 v[2:5], v[18:19], off offset:128
	v_or_b32_e32 v18, 0x10200, v67
	ds_read_b128 v[52:55], v18
	v_or_b32_e32 v39, 0x10210, v67
	v_lshlrev_b32_e32 v43, 4, v46
	v_and_b32_e32 v43, 0xffffff80, v43
	v_and_b32_e32 v0, 15, v46
	s_waitcnt vmcnt(0) lgkmcnt(0)
	v_lshlrev_b32_e32 v18, 16, v22
	v_and_b32_e32 v19, 0xffff0000, v22
	v_pk_mul_f32 v[18:19], v[52:53], v[18:19]
	v_lshlrev_b32_e32 v20, 16, v26
	v_and_b32_e32 v21, 0xffff0000, v26
	v_pk_mul_f32 v[20:21], v[52:53], v[20:21]
	v_cvt_pk_bf16_f32 v18, v18, v19
	v_cvt_pk_bf16_f32 v22, v20, v21
	v_lshlrev_b32_e32 v20, 16, v30
	v_and_b32_e32 v21, 0xffff0000, v30
	v_pk_mul_f32 v[20:21], v[52:53], v[20:21]
	s_nop 0
	v_cvt_pk_bf16_f32 v26, v20, v21
	v_lshlrev_b32_e32 v20, 16, v48
	v_and_b32_e32 v21, 0xffff0000, v48
	v_pk_mul_f32 v[20:21], v[52:53], v[20:21]
	v_lshlrev_b32_e32 v48, 16, v28
	v_cvt_pk_bf16_f32 v30, v20, v21
	v_lshlrev_b32_e32 v20, 16, v23
	v_and_b32_e32 v21, 0xffff0000, v23
	v_pk_mul_f32 v[20:21], v[54:55], v[20:21]
	s_nop 0
	v_cvt_pk_bf16_f32 v19, v20, v21
	v_lshlrev_b32_e32 v20, 16, v27
	v_and_b32_e32 v21, 0xffff0000, v27
	v_pk_mul_f32 v[20:21], v[54:55], v[20:21]
	s_nop 0
	v_cvt_pk_bf16_f32 v23, v20, v21
	v_lshlrev_b32_e32 v20, 16, v31
	v_and_b32_e32 v21, 0xffff0000, v31
	v_pk_mul_f32 v[20:21], v[54:55], v[20:21]
	s_nop 0
	v_cvt_pk_bf16_f32 v27, v20, v21
	v_lshlrev_b32_e32 v20, 16, v49
	v_and_b32_e32 v21, 0xffff0000, v49
	v_pk_mul_f32 v[20:21], v[54:55], v[20:21]
	ds_read_b128 v[52:55], v39
	v_and_b32_e32 v49, 0xffff0000, v28
	v_cvt_pk_bf16_f32 v31, v20, v21
	v_lshlrev_b32_e32 v20, 16, v24
	v_and_b32_e32 v21, 0xffff0000, v24
	s_waitcnt lgkmcnt(0)
	v_pk_mul_f32 v[48:49], v[52:53], v[48:49]
	v_pk_mul_f32 v[20:21], v[52:53], v[20:21]
	v_cvt_pk_bf16_f32 v24, v48, v49
	v_lshlrev_b32_e32 v48, 16, v32
	v_and_b32_e32 v49, 0xffff0000, v32
	v_pk_mul_f32 v[48:49], v[52:53], v[48:49]
	v_cvt_pk_bf16_f32 v20, v20, v21
	v_cvt_pk_bf16_f32 v28, v48, v49
	v_lshlrev_b32_e32 v48, 16, v50
	v_and_b32_e32 v49, 0xffff0000, v50
	v_pk_mul_f32 v[48:49], v[52:53], v[48:49]
	v_xor_b32_e32 v39, v47, v46
	v_cvt_pk_bf16_f32 v32, v48, v49
	v_lshlrev_b32_e32 v48, 16, v25
	v_and_b32_e32 v49, 0xffff0000, v25
	v_pk_mul_f32 v[48:49], v[54:55], v[48:49]
	v_lshlrev_b32_e32 v39, 4, v39
	v_cvt_pk_bf16_f32 v21, v48, v49
	v_lshlrev_b32_e32 v48, 16, v29
	v_and_b32_e32 v49, 0xffff0000, v29
	v_pk_mul_f32 v[48:49], v[54:55], v[48:49]
	v_and_or_b32 v68, v39, s14, v43
	v_cvt_pk_bf16_f32 v25, v48, v49
	v_lshlrev_b32_e32 v48, 16, v33
	v_and_b32_e32 v49, 0xffff0000, v33
	v_pk_mul_f32 v[48:49], v[54:55], v[48:49]
	v_lshlrev_b32_e32 v43, 7, v0
	v_cvt_pk_bf16_f32 v29, v48, v49
	v_lshlrev_b32_e32 v48, 16, v51
	v_and_b32_e32 v49, 0xffff0000, v51
	v_pk_mul_f32 v[48:49], v[54:55], v[48:49]
	v_lshl_or_b32 v107, v65, 13, v43
	v_cvt_pk_bf16_f32 v33, v48, v49
	ds_write_b128 v68, v[18:21]
	ds_write_b128 v68, v[22:25] offset:4096
	ds_write_b128 v68, v[26:29] offset:8192
	ds_write_b128 v68, v[30:33] offset:12288
	v_and_b32_e32 v22, -8, v44
	v_lshlrev_b32_e32 v18, 5, v45
	v_lshlrev_b32_e32 v24, 9, v45
	v_bitop3_b32 v25, v18, v22, 32 bitop3:0x6c
	v_and_b32_e32 v23, 7, v44
	v_add_u32_e32 v18, v25, v24
	v_or_b32_e32 v18, v18, v23
	v_lshlrev_b32_e32 v69, 1, v18
	global_load_dwordx4 v[18:21], v[34:35], off offset:512
	v_or_b32_e32 v24, v23, v24
	v_add_lshl_u32 v70, v24, v25, 1
	v_bitop3_b32 v26, v47, v106, 3 bitop3:0x6c
	v_lshl_or_b32 v110, v64, 12, v43
	v_lshlrev_b32_e32 v0, 2, v0
	v_lshl_or_b32 v0, v64, 7, v0
	s_waitcnt vmcnt(0) lgkmcnt(0)
	ds_write_b16 v69, v18 offset:16384
	ds_write_b16_d16_hi v70, v18 offset:16512
	v_or_b32_e32 v18, 2, v42
	v_lshlrev_b32_e32 v24, 6, v18
	v_lshlrev_b32_e32 v18, 2, v18
	v_and_b32_e32 v18, 40, v18
	v_xad_u32 v18, v18, v22, v24
	v_or_b32_e32 v18, v18, v23
	v_lshlrev_b32_e32 v71, 1, v18
	v_or_b32_e32 v18, 3, v42
	v_lshlrev_b32_e32 v24, 6, v18
	v_lshlrev_b32_e32 v18, 2, v18
	v_and_b32_e32 v18, 40, v18
	v_xad_u32 v18, v18, v22, v24
	v_or_b32_e32 v18, v18, v23
	v_lshlrev_b32_e32 v72, 1, v18
	v_or_b32_e32 v18, 4, v42
	ds_write_b16 v71, v19 offset:16384
	ds_write_b16_d16_hi v72, v19 offset:16384
	v_lshlrev_b32_e32 v19, 6, v18
	v_lshlrev_b32_e32 v18, 2, v18
	v_and_b32_e32 v18, 48, v18
	v_xad_u32 v18, v18, v22, v19
	v_or_b32_e32 v18, v18, v23
	v_lshlrev_b32_e32 v73, 1, v18
	v_or_b32_e32 v18, 5, v42
	v_lshlrev_b32_e32 v19, 6, v18
	v_lshlrev_b32_e32 v18, 2, v18
	v_and_b32_e32 v18, 48, v18
	v_xad_u32 v18, v18, v22, v19
	v_or_b32_e32 v18, v18, v23
	v_lshlrev_b32_e32 v74, 1, v18
	v_or_b32_e32 v18, 6, v42
	v_lshlrev_b32_e32 v19, 6, v18
	v_lshlrev_b32_e32 v18, 2, v18
	v_and_b32_e32 v18, 56, v18
	v_xad_u32 v18, v18, v22, v19
	v_or_b32_e32 v18, v18, v23
	v_lshlrev_b32_e32 v75, 1, v18
	v_or_b32_e32 v18, 7, v42
	v_lshlrev_b32_e32 v19, 6, v18
	v_lshlrev_b32_e32 v18, 2, v18
	v_and_b32_e32 v18, 56, v18
	v_xad_u32 v18, v18, v22, v19
	v_or_b32_e32 v18, v18, v23
	v_lshlrev_b32_e32 v76, 1, v18
	v_and_b32_e32 v22, -8, v40
	v_lshlrev_b32_e32 v18, 5, v41
	v_lshlrev_b32_e32 v24, 9, v41
	v_bitop3_b32 v25, v18, v22, 32 bitop3:0x6c
	v_and_b32_e32 v23, 7, v40
	v_add_u32_e32 v18, v25, v24
	v_or_b32_e32 v18, v18, v23
	ds_write_b16 v73, v20 offset:16384
	ds_write_b16_d16_hi v74, v20 offset:16384
	ds_write_b16 v75, v21 offset:16384
	ds_write_b16_d16_hi v76, v21 offset:16384
	v_lshlrev_b32_e32 v77, 1, v18
	global_load_dwordx4 v[18:21], v[36:37], off offset:512
	v_or_b32_e32 v24, v23, v24
	v_add_lshl_u32 v78, v24, v25, 1
	v_lshlrev_b32_e32 v42, 4, v26
	v_or_b32_e32 v121, v42, v107
	v_or_b32_e32 v122, v42, v110
	s_waitcnt vmcnt(0) lgkmcnt(0)
	ds_write_b16 v77, v18 offset:16384
	ds_write_b16_d16_hi v78, v18 offset:16512
	v_or_b32_e32 v18, 2, v38
	v_lshlrev_b32_e32 v24, 6, v18
	v_lshlrev_b32_e32 v18, 2, v18
	v_and_b32_e32 v18, 40, v18
	v_xad_u32 v18, v18, v22, v24
	v_or_b32_e32 v18, v18, v23
	v_lshlrev_b32_e32 v79, 1, v18
	v_or_b32_e32 v18, 3, v38
	v_lshlrev_b32_e32 v24, 6, v18
	v_lshlrev_b32_e32 v18, 2, v18
	v_and_b32_e32 v18, 40, v18
	v_xad_u32 v18, v18, v22, v24
	v_or_b32_e32 v18, v18, v23
	v_lshlrev_b32_e32 v80, 1, v18
	v_or_b32_e32 v18, 4, v38
	ds_write_b16 v79, v19 offset:16384
	ds_write_b16_d16_hi v80, v19 offset:16384
	v_lshlrev_b32_e32 v19, 6, v18
	v_lshlrev_b32_e32 v18, 2, v18
	v_and_b32_e32 v18, 48, v18
	v_xad_u32 v18, v18, v22, v19
	v_or_b32_e32 v18, v18, v23
	v_lshlrev_b32_e32 v81, 1, v18
	v_or_b32_e32 v18, 5, v38
	v_lshlrev_b32_e32 v19, 6, v18
	v_lshlrev_b32_e32 v18, 2, v18
	v_and_b32_e32 v18, 48, v18
	v_xad_u32 v18, v18, v22, v19
	v_or_b32_e32 v18, v18, v23
	v_lshlrev_b32_e32 v118, 1, v18
	v_or_b32_e32 v18, 6, v38
	v_lshlrev_b32_e32 v19, 6, v18
	v_lshlrev_b32_e32 v18, 2, v18
	v_and_b32_e32 v18, 56, v18
	v_xad_u32 v18, v18, v22, v19
	v_or_b32_e32 v18, v18, v23
	v_lshlrev_b32_e32 v119, 1, v18
	v_or_b32_e32 v18, 7, v38
	v_lshlrev_b32_e32 v19, 6, v18
	v_lshlrev_b32_e32 v18, 2, v18
	v_and_b32_e32 v18, 56, v18
	v_xad_u32 v18, v18, v22, v19
	v_or_b32_e32 v18, v18, v23
	v_lshlrev_b32_e32 v120, 1, v18
	v_add_co_u32_e32 v18, vcc, s16, v34
	ds_write_b16 v81, v20 offset:16384
	s_nop 0
	v_addc_co_u32_e32 v19, vcc, 0, v35, vcc
	ds_write_b16_d16_hi v118, v20 offset:16384
	ds_write_b16 v119, v21 offset:16384
	ds_write_b16_d16_hi v120, v21 offset:16384
	global_load_dwordx4 v[18:21], v[18:19], off offset:512
	v_add_co_u32_e32 v22, vcc, s16, v36
	s_nop 1
	v_addc_co_u32_e32 v23, vcc, 0, v37, vcc
	global_load_dwordx4 v[22:25], v[22:23], off offset:512
	s_waitcnt lgkmcnt(0)
	s_barrier
	ds_read_b128 v[26:29], v121
	ds_read_b128 v[30:33], v121 offset:2048
	ds_read_b128 v[34:37], v121 offset:4096
	ds_read_b128 v[38:41], v121 offset:6144
	ds_read_b128 v[42:45], v122 offset:16384
	ds_read_b128 v[46:49], v122 offset:18432
	s_waitcnt lgkmcnt(0)
	v_mfma_f32_16x16x32_bf16 v[50:53], v[26:29], v[42:45], 0
	v_mfma_f32_16x16x32_bf16 v[54:57], v[26:29], v[46:49], 0
	v_bitop3_b32 v26, v66, v106, 4 bitop3:0x36
	v_lshlrev_b32_e32 v26, 4, v26
	v_or_b32_e32 v123, v26, v107
	v_or_b32_e32 v124, v26, v110
	v_mfma_f32_16x16x32_bf16 v[82:85], v[30:33], v[42:45], 0
	v_mfma_f32_16x16x32_bf16 v[86:89], v[30:33], v[46:49], 0
	v_mfma_f32_16x16x32_bf16 v[94:97], v[34:37], v[46:49], 0
	v_mfma_f32_16x16x32_bf16 v[98:101], v[38:41], v[42:45], 0
	v_mfma_f32_16x16x32_bf16 v[102:105], v[38:41], v[46:49], 0
	ds_read_b128 v[30:33], v123
	ds_read_b128 v[38:41], v123 offset:2048
	ds_read_b128 v[46:49], v123 offset:4096
	ds_read_b128 v[106:109], v123 offset:6144
	ds_read_b128 v[110:113], v124 offset:16384
	ds_read_b128 v[114:117], v124 offset:18432
	v_mfma_f32_16x16x32_bf16 v[90:93], v[34:37], v[42:45], 0
	s_waitcnt lgkmcnt(0)
	v_mfma_f32_16x16x32_bf16 v[34:37], v[38:41], v[110:113], v[82:85]
	s_nop 2
	v_or_b32_e32 v82, 0x10300, v67
	ds_read_b128 v[82:85], v82
	v_mfma_f32_16x16x32_bf16 v[38:41], v[38:41], v[114:117], v[86:89]
	v_or_b32_e32 v67, 0x10310, v67
	s_nop 1
	v_lshlrev_b32_e32 v86, 16, v14
	v_and_b32_e32 v87, 0xffff0000, v14
	s_waitcnt lgkmcnt(0)
; __device__ __forceinline__ int tid_() { int t = threadIdx.x; asm volatile("" : "+v"(t)); return t; }
; __device__ __forceinline__ void phase_mix_a(const Params& p, int l, bool last, unsigned char* smem) {
;     ...
;       auto epi = [&](f32x4(&acc)[4][2], int r0, int c0) {
;         float* Ts = (float*)smem;
;         const int t2 = tid_();
;         __syncthreads();
; #pragma unroll
;         for (int mi = 0; mi < 4; ++mi)
; #pragma unroll
;           for (int ni = 0; ni < 2; ++ni)
; #pragma unroll
;             for (int j = 0; j < 4; ++j) {
;               const int pr = r0 + mi * 16 + j;
;               Ts[pr * 68 + c0 + ni * 16] = acc[mi][ni][j] * sgn[c0 + ni * 16] + bs[pr];
	v_pk_mul_f32 v[86:87], v[82:83], v[86:87]
	v_mfma_f32_16x16x32_bf16 v[26:29], v[30:33], v[110:113], v[50:53]
	v_cvt_pk_bf16_f32 v14, v86, v87
	v_lshlrev_b32_e32 v86, 16, v10
	v_and_b32_e32 v87, 0xffff0000, v10
	v_pk_mul_f32 v[86:87], v[82:83], v[86:87]
	v_mfma_f32_16x16x32_bf16 v[30:33], v[30:33], v[114:117], v[54:57]
	v_cvt_pk_bf16_f32 v10, v86, v87
	v_lshlrev_b32_e32 v86, 16, v6
	v_and_b32_e32 v87, 0xffff0000, v6
	v_pk_mul_f32 v[86:87], v[82:83], v[86:87]
	v_mfma_f32_16x16x32_bf16 v[42:45], v[46:49], v[110:113], v[90:93]
	v_cvt_pk_bf16_f32 v6, v86, v87
	v_lshlrev_b32_e32 v86, 16, v2
	v_and_b32_e32 v87, 0xffff0000, v2
	v_pk_mul_f32 v[82:83], v[82:83], v[86:87]
	v_lshlrev_b32_e32 v86, 16, v16
	v_cvt_pk_bf16_f32 v2, v82, v83
	v_lshlrev_b32_e32 v82, 16, v15
	v_and_b32_e32 v83, 0xffff0000, v15
	v_pk_mul_f32 v[82:83], v[84:85], v[82:83]
	v_and_b32_e32 v87, 0xffff0000, v16
	v_cvt_pk_bf16_f32 v15, v82, v83
	v_lshlrev_b32_e32 v82, 16, v11
	v_and_b32_e32 v83, 0xffff0000, v11
	v_pk_mul_f32 v[82:83], v[84:85], v[82:83]
	v_mfma_f32_16x16x32_bf16 v[46:49], v[46:49], v[114:117], v[94:97]
	v_cvt_pk_bf16_f32 v11, v82, v83
	v_lshlrev_b32_e32 v82, 16, v7
	v_and_b32_e32 v83, 0xffff0000, v7
	v_pk_mul_f32 v[82:83], v[84:85], v[82:83]
	v_mfma_f32_16x16x32_bf16 v[50:53], v[106:109], v[110:113], v[98:101]
	v_cvt_pk_bf16_f32 v7, v82, v83
	v_lshlrev_b32_e32 v82, 16, v3
	v_and_b32_e32 v83, 0xffff0000, v3
	v_pk_mul_f32 v[82:83], v[84:85], v[82:83]
	v_mfma_f32_16x16x32_bf16 v[54:57], v[106:109], v[114:117], v[102:105]
	v_cvt_pk_bf16_f32 v3, v82, v83
	ds_read_b128 v[82:85], v67
	s_waitcnt lgkmcnt(0)
	v_pk_mul_f32 v[86:87], v[82:83], v[86:87]
	s_nop 0
	v_cvt_pk_bf16_f32 v16, v86, v87
	v_lshlrev_b32_e32 v86, 16, v12
	v_and_b32_e32 v87, 0xffff0000, v12
	v_pk_mul_f32 v[86:87], v[82:83], v[86:87]
	s_nop 0
	v_cvt_pk_bf16_f32 v12, v86, v87
	v_lshlrev_b32_e32 v86, 16, v8
	v_and_b32_e32 v87, 0xffff0000, v8
	v_pk_mul_f32 v[86:87], v[82:83], v[86:87]
	s_nop 0
	v_cvt_pk_bf16_f32 v8, v86, v87
	v_lshlrev_b32_e32 v86, 16, v4
	v_and_b32_e32 v87, 0xffff0000, v4
	v_pk_mul_f32 v[82:83], v[82:83], v[86:87]
	s_nop 0
	v_cvt_pk_bf16_f32 v4, v82, v83
	v_lshlrev_b32_e32 v82, 16, v17
	v_and_b32_e32 v83, 0xffff0000, v17
	v_pk_mul_f32 v[82:83], v[84:85], v[82:83]
	s_nop 0
	v_cvt_pk_bf16_f32 v17, v82, v83
	v_lshlrev_b32_e32 v82, 16, v13
	v_and_b32_e32 v83, 0xffff0000, v13
	v_pk_mul_f32 v[82:83], v[84:85], v[82:83]
	s_nop 0
	v_cvt_pk_bf16_f32 v13, v82, v83
	v_lshlrev_b32_e32 v82, 16, v9
	v_and_b32_e32 v83, 0xffff0000, v9
	v_pk_mul_f32 v[82:83], v[84:85], v[82:83]
	s_nop 0
	v_cvt_pk_bf16_f32 v9, v82, v83
	v_lshlrev_b32_e32 v82, 16, v5
	v_and_b32_e32 v83, 0xffff0000, v5
	v_pk_mul_f32 v[82:83], v[84:85], v[82:83]
	s_nop 0
	v_cvt_pk_bf16_f32 v5, v82, v83
	ds_write_b128 v68, v[14:17] offset:32768
	ds_write_b128 v68, v[10:13] offset:36864
	ds_write_b128 v68, v[6:9] offset:40960
	ds_write_b128 v68, v[2:5] offset:45056
	s_waitcnt vmcnt(0)
	ds_write_b16 v69, v18 offset:49152
	ds_write_b16_d16_hi v70, v18 offset:49280
	ds_write_b16 v71, v19 offset:49152
	ds_write_b16_d16_hi v72, v19 offset:49152
	ds_write_b16 v73, v20 offset:49152
	ds_write_b16_d16_hi v74, v20 offset:49152
	ds_write_b16 v75, v21 offset:49152
	ds_write_b16_d16_hi v76, v21 offset:49152
	ds_write_b16 v77, v22 offset:49152
	ds_write_b16_d16_hi v78, v22 offset:49280
	ds_write_b16 v79, v23 offset:49152
	ds_write_b16_d16_hi v80, v23 offset:49152
	ds_write_b16 v81, v24 offset:49152
	ds_write_b16_d16_hi v118, v24 offset:49152
	ds_write_b16 v119, v25 offset:49152
	ds_write_b16_d16_hi v120, v25 offset:49152
	s_waitcnt lgkmcnt(0)
	s_barrier
	ds_read_b128 v[2:5], v121 offset:32768
	ds_read_b128 v[6:9], v121 offset:34816
	ds_read_b128 v[10:13], v121 offset:36864
	ds_read_b128 v[14:17], v121 offset:38912
	ds_read_b128 v[18:21], v122 offset:49152
	ds_read_b128 v[22:25], v122 offset:51200
	s_waitcnt lgkmcnt(1)
	v_mfma_f32_16x16x32_bf16 v[26:29], v[2:5], v[18:21], v[26:29]
	s_waitcnt lgkmcnt(0)
	v_mfma_f32_16x16x32_bf16 v[2:5], v[2:5], v[22:25], v[30:33]
	v_mfma_f32_16x16x32_bf16 v[30:33], v[6:9], v[18:21], v[34:37]
	v_mfma_f32_16x16x32_bf16 v[6:9], v[6:9], v[22:25], v[38:41]
	v_mfma_f32_16x16x32_bf16 v[34:37], v[10:13], v[18:21], v[42:45]
	v_mfma_f32_16x16x32_bf16 v[10:13], v[10:13], v[22:25], v[46:49]
	v_mfma_f32_16x16x32_bf16 v[18:21], v[14:17], v[18:21], v[50:53]
	v_mfma_f32_16x16x32_bf16 v[14:17], v[14:17], v[22:25], v[54:57]
	ds_read_b128 v[22:25], v123 offset:32768
	ds_read_b128 v[38:41], v123 offset:34816
	ds_read_b128 v[42:45], v123 offset:36864
	ds_read_b128 v[46:49], v123 offset:38912
	ds_read_b128 v[50:53], v124 offset:49152
	ds_read_b128 v[54:57], v124 offset:51200
	s_waitcnt lgkmcnt(1)
	v_mfma_f32_16x16x32_bf16 v[26:29], v[22:25], v[50:53], v[26:29]
	s_waitcnt lgkmcnt(0)
	v_mfma_f32_16x16x32_bf16 v[22:25], v[22:25], v[54:57], v[2:5]
	v_mfma_f32_16x16x32_bf16 v[2:5], v[46:49], v[54:57], v[14:17]
	s_nop 2
	v_lshlrev_b32_e32 v14, 6, v65
	v_mfma_f32_16x16x32_bf16 v[30:33], v[38:41], v[50:53], v[30:33]
	v_mfma_f32_16x16x32_bf16 v[38:41], v[38:41], v[54:57], v[6:9]
	v_mfma_f32_16x16x32_bf16 v[6:9], v[46:49], v[50:53], v[18:21]
	s_nop 2
	v_lshl_or_b32 v18, v66, 2, v14
	v_ashrrev_i32_e32 v19, 31, v18
	v_mov_b32_e32 v20, v187
	v_lshl_add_u64 v[14:15], v[62:63], 0, v[0:1]
	v_lshl_add_u64 v[16:17], v[18:19], 2, v[60:61]
	s_barrier
; __device__ __forceinline__ int tid_() { int t = threadIdx.x; asm volatile("" : "+v"(t)); return t; }
; __device__ __forceinline__ void phase_mix_a(const Params& p, int l, bool last, unsigned char* smem) {
;     ...
;       auto epi = [&](f32x4(&acc)[4][2], int r0, int c0) {
;         float* Ts = (float*)smem;
;         const int t2 = tid_();
;         __syncthreads();
; #pragma unroll
;         for (int mi = 0; mi < 4; ++mi)
; #pragma unroll
;           for (int ni = 0; ni < 2; ++ni)
; #pragma unroll
;             for (int j = 0; j < 4; ++j) {
;               const int pr = r0 + mi * 16 + j;
;               Ts[pr * 68 + c0 + ni * 16] = acc[mi][ni][j] * sgn[c0 + ni * 16] + bs[pr];
;             }
;         __syncthreads();
	global_load_dword v100, v[14:15], off
	global_load_dword v101, v[14:15], off offset:64
	global_load_dwordx4 v[104:107], v[16:17], off offset:0
	global_load_dwordx4 v[108:111], v[16:17], off offset:64
	global_load_dwordx4 v[112:115], v[16:17], off offset:128
	global_load_dwordx4 v[116:119], v[16:17], off offset:192
	s_waitcnt vmcnt(0)
	v_mov_b32_e32 v21, v100
	v_mov_b32_e32 v19, v104
	v_mfma_f32_16x16x32_bf16 v[34:37], v[42:45], v[50:53], v[34:37]
	s_waitcnt lgkmcnt(0)
	v_fmac_f32_e32 v19, v26, v21
	v_mfma_f32_16x16x32_bf16 v[10:13], v[42:45], v[54:57], v[10:13]
	v_mad_u64_u32 v[42:43], s[34:35], v18, s23, v[0:1]
	ds_write_b32 v42, v19
	v_mov_b32_e32 v19, v100
	v_mov_b32_e32 v21, v105
	v_or_b32_e32 v18, 1, v18
	s_waitcnt lgkmcnt(0)
	v_fmac_f32_e32 v21, v27, v19
	v_mad_u64_u32 v[18:19], s[34:35], v18, s23, v[0:1]
	ds_write_b32 v18, v21
	v_mov_b32_e32 v0, v100
	v_mov_b32_e32 v19, v106
	s_waitcnt lgkmcnt(0)
	v_fmac_f32_e32 v19, v28, v0
	ds_write_b32 v18, v19 offset:272
	v_mov_b32_e32 v0, v100
	v_mov_b32_e32 v19, v107
	s_waitcnt lgkmcnt(0)
	v_fmac_f32_e32 v19, v29, v0
	ds_write_b32 v18, v19 offset:544
	v_mov_b32_e32 v0, v101
	v_mov_b32_e32 v19, v104
	s_waitcnt lgkmcnt(0)
	v_fmac_f32_e32 v19, v22, v0
	ds_write_b32 v42, v19 offset:64
	v_mov_b32_e32 v0, v101
	v_mov_b32_e32 v19, v105
	s_waitcnt lgkmcnt(0)
	v_fmac_f32_e32 v19, v23, v0
	ds_write_b32 v18, v19 offset:64
	v_mov_b32_e32 v0, v101
	v_mov_b32_e32 v19, v106
	s_waitcnt lgkmcnt(0)
	v_fmac_f32_e32 v19, v24, v0
	ds_write_b32 v18, v19 offset:336
	v_mov_b32_e32 v0, v101
	v_mov_b32_e32 v19, v107
	s_waitcnt lgkmcnt(0)
	v_fmac_f32_e32 v19, v25, v0
	ds_write_b32 v18, v19 offset:608
	v_mov_b32_e32 v0, v100
	v_mov_b32_e32 v19, v108
	s_waitcnt lgkmcnt(0)
	v_fmac_f32_e32 v19, v30, v0
	ds_write_b32 v18, v19 offset:4080
	v_mov_b32_e32 v0, v100
	v_mov_b32_e32 v19, v109
	s_waitcnt lgkmcnt(0)
	v_fmac_f32_e32 v19, v31, v0
	ds_write_b32 v18, v19 offset:4352
	v_mov_b32_e32 v0, v100
	v_mov_b32_e32 v19, v110
	s_waitcnt lgkmcnt(0)
	v_fmac_f32_e32 v19, v32, v0
	ds_write_b32 v18, v19 offset:4624
	v_mov_b32_e32 v0, v100
	v_mov_b32_e32 v19, v111
	s_waitcnt lgkmcnt(0)
	v_fmac_f32_e32 v19, v33, v0
	ds_write_b32 v18, v19 offset:4896
	v_mov_b32_e32 v0, v101
	v_mov_b32_e32 v19, v108
	s_waitcnt lgkmcnt(0)
	v_fmac_f32_e32 v19, v38, v0
	ds_write_b32 v18, v19 offset:4144
	v_mov_b32_e32 v0, v101
	v_mov_b32_e32 v19, v109
	s_waitcnt lgkmcnt(0)
	v_fmac_f32_e32 v19, v39, v0
	ds_write_b32 v18, v19 offset:4416
	v_mov_b32_e32 v0, v101
	v_mov_b32_e32 v19, v110
	s_waitcnt lgkmcnt(0)
	v_fmac_f32_e32 v19, v40, v0
	ds_write_b32 v18, v19 offset:4688
	v_mov_b32_e32 v0, v101
	v_mov_b32_e32 v19, v111
	s_waitcnt lgkmcnt(0)
	v_fmac_f32_e32 v19, v41, v0
	ds_write_b32 v18, v19 offset:4960
	v_mov_b32_e32 v0, v100
	v_mov_b32_e32 v19, v112
	s_waitcnt lgkmcnt(0)
	v_fmac_f32_e32 v19, v34, v0
	ds_write_b32 v18, v19 offset:8432
	v_mov_b32_e32 v0, v100
	v_mov_b32_e32 v19, v113
	s_waitcnt lgkmcnt(0)
	v_fmac_f32_e32 v19, v35, v0
	ds_write_b32 v18, v19 offset:8704
	v_mov_b32_e32 v0, v100
	v_mov_b32_e32 v19, v114
	s_waitcnt lgkmcnt(0)
	v_fmac_f32_e32 v19, v36, v0
	ds_write_b32 v18, v19 offset:8976
	v_mov_b32_e32 v0, v100
	v_mov_b32_e32 v19, v115
	s_waitcnt lgkmcnt(0)
	v_fmac_f32_e32 v19, v37, v0
	ds_write_b32 v18, v19 offset:9248
	v_mov_b32_e32 v0, v101
	v_mov_b32_e32 v19, v112
	s_waitcnt lgkmcnt(0)
	v_fmac_f32_e32 v19, v10, v0
	ds_write_b32 v18, v19 offset:8496
	v_mov_b32_e32 v0, v101
	v_mov_b32_e32 v10, v113
	s_waitcnt lgkmcnt(0)
	v_fmac_f32_e32 v10, v11, v0
	ds_write_b32 v18, v10 offset:8768
	v_mov_b32_e32 v0, v101
	v_mov_b32_e32 v10, v114
	s_waitcnt lgkmcnt(0)
	v_fmac_f32_e32 v10, v12, v0
	ds_write_b32 v18, v10 offset:9040
	v_mov_b32_e32 v0, v101
	v_mov_b32_e32 v10, v115
	s_waitcnt lgkmcnt(0)
	v_fmac_f32_e32 v10, v13, v0
	ds_write_b32 v18, v10 offset:9312
	v_mov_b32_e32 v0, v100
	v_mov_b32_e32 v10, v116
	s_waitcnt lgkmcnt(0)
	v_fmac_f32_e32 v10, v6, v0
	ds_write_b32 v18, v10 offset:12784
	v_mov_b32_e32 v0, v100
	v_mov_b32_e32 v6, v117
	s_waitcnt lgkmcnt(0)
	v_fmac_f32_e32 v6, v7, v0
	ds_write_b32 v18, v6 offset:13056
	v_mov_b32_e32 v0, v100
	v_mov_b32_e32 v6, v118
	s_waitcnt lgkmcnt(0)
	v_fmac_f32_e32 v6, v8, v0
	ds_write_b32 v18, v6 offset:13328
	v_mov_b32_e32 v0, v100
	v_mov_b32_e32 v6, v119
	s_waitcnt lgkmcnt(0)
	v_fmac_f32_e32 v6, v9, v0
	ds_write_b32 v18, v6 offset:13600
	v_mov_b32_e32 v0, v101
	v_mov_b32_e32 v6, v116
	s_waitcnt lgkmcnt(0)
	v_fmac_f32_e32 v6, v2, v0
	ds_write_b32 v18, v6 offset:12848
	v_mov_b32_e32 v0, v101
	v_mov_b32_e32 v2, v117
	s_waitcnt lgkmcnt(0)
	v_fmac_f32_e32 v2, v3, v0
	ds_write_b32 v18, v2 offset:13120
	v_mov_b32_e32 v0, v101
	v_mov_b32_e32 v2, v118
	v_ashrrev_i32_e32 v3, 3, v20
	s_waitcnt lgkmcnt(0)
	v_fmac_f32_e32 v2, v4, v0
	ds_write_b32 v18, v2 offset:13392
	v_mov_b32_e32 v0, v101
	v_mov_b32_e32 v2, v119
	v_add_u32_e32 v4, s38, v3
	s_waitcnt lgkmcnt(0)
	v_fmac_f32_e32 v2, v5, v0
	v_ashrrev_i32_e32 v5, 31, v4
	ds_write_b32 v18, v2 offset:13664
	s_waitcnt lgkmcnt(0)
	s_barrier
; __device__ __forceinline__ float bf2f(u16 b) { return __uint_as_float(((unsigned)b) << 16); }
; __device__ __forceinline__ void phase_mix_a(const Params& p, int l, bool last, unsigned char* smem) {
;     ...
; #pragma unroll
;         for (int i = 0; i < 4; ++i) {
;           const int c = t2 + 256 * i, pr = c >> 3, ch = c & 7;
;           const size_t o = (size_t)(row_base + pr) * 1024 + h * 64 + ch * 8;
;           const u32x4 u = *(const u32x4*)(p.PX + o);
;           const float4 z0 = *(const float4*)(Ts + pr * 68 + ch * 8), z1 = *(const float4*)(Ts + pr * 68 + ch * 8 + 4);
;           u32x4 r;
;           r.x = pack2(bf2f((u16)(u.x & 0xffffu)) * z0.x, bf2f((u16)(u.x >> 16)) * z0.y);
;           r.y = pack2(bf2f((u16)(u.y & 0xffffu)) * z0.z, bf2f((u16)(u.y >> 16)) * z0.w);
;           r.z = pack2(bf2f((u16)(u.z & 0xffffu)) * z1.x, bf2f((u16)(u.z >> 16)) * z1.y);
;           r.w = pack2(bf2f((u16)(u.w & 0xffffu)) * z1.z, bf2f((u16)(u.w >> 16)) * z1.w);
;           *(u32x4*)(p.YM + o) = r;
;         }
	v_lshlrev_b64 v[8:9], 10, v[4:5]
	global_load_dwordx4 v[4:7], v[58:59], off offset:288
	v_lshlrev_b32_e32 v0, 3, v20
	v_and_b32_e32 v2, 56, v0
	v_or3_b32 v8, v8, s0, v2
	v_lshlrev_b64 v[22:23], 1, v[8:9]
	v_lshlrev_b32_e32 v0, 2, v2
	s_waitcnt vmcnt(0) lgkmcnt(0)
	v_lshl_add_u64 v[4:5], v[4:5], 0, v[22:23]
	global_load_dwordx4 v[8:11], v[4:5], off
	v_mad_u64_u32 v[4:5], s[34:35], v3, s23, v[0:1]
	ds_read_b128 v[12:15], v4
	ds_read_b128 v[16:19], v4 offset:16
	v_add_u32_e32 v3, 0x100, v20
	v_ashrrev_i32_e32 v3, 3, v3
	s_waitcnt vmcnt(0) lgkmcnt(0)
	v_and_b32_e32 v5, 0xffff0000, v8
	v_lshlrev_b32_e32 v4, 16, v8
	v_pk_mul_f32 v[4:5], v[12:13], v[4:5]
	s_nop 0
	v_cvt_pk_bf16_f32 v8, v4, v5
	v_and_b32_e32 v5, 0xffff0000, v9
	v_lshlrev_b32_e32 v4, 16, v9
	v_pk_mul_f32 v[4:5], v[14:15], v[4:5]
	s_nop 0
	v_cvt_pk_bf16_f32 v9, v4, v5
	v_and_b32_e32 v5, 0xffff0000, v10
	v_lshlrev_b32_e32 v4, 16, v10
	v_pk_mul_f32 v[4:5], v[16:17], v[4:5]
	s_nop 0
	v_cvt_pk_bf16_f32 v10, v4, v5
	v_and_b32_e32 v5, 0xffff0000, v11
	v_lshlrev_b32_e32 v4, 16, v11
	v_pk_mul_f32 v[4:5], v[18:19], v[4:5]
	s_nop 0
	v_cvt_pk_bf16_f32 v11, v4, v5
	v_lshl_add_u64 v[4:5], v[6:7], 0, v[22:23]
	global_store_dwordx4 v[4:5], v[8:11], off
	v_add_u32_e32 v4, s38, v3
	v_ashrrev_i32_e32 v5, 31, v4
	v_lshlrev_b64 v[8:9], 10, v[4:5]
	global_load_dwordx4 v[4:7], v[58:59], off offset:288
	v_or3_b32 v8, v8, s0, v2
	v_lshlrev_b64 v[22:23], 1, v[8:9]
	s_waitcnt vmcnt(0) lgkmcnt(0)
	v_lshl_add_u64 v[4:5], v[4:5], 0, v[22:23]
	global_load_dwordx4 v[8:11], v[4:5], off
	v_mad_u64_u32 v[4:5], s[34:35], v3, s23, v[0:1]
	ds_read_b128 v[12:15], v4
	ds_read_b128 v[16:19], v4 offset:16
	v_add_u32_e32 v3, 0x200, v20
	v_ashrrev_i32_e32 v3, 3, v3
	s_waitcnt vmcnt(0) lgkmcnt(0)
	v_and_b32_e32 v5, 0xffff0000, v8
	v_lshlrev_b32_e32 v4, 16, v8
	v_pk_mul_f32 v[4:5], v[12:13], v[4:5]
	s_nop 0
	v_cvt_pk_bf16_f32 v8, v4, v5
	v_and_b32_e32 v5, 0xffff0000, v9
	v_lshlrev_b32_e32 v4, 16, v9
	v_pk_mul_f32 v[4:5], v[14:15], v[4:5]
	s_nop 0
	v_cvt_pk_bf16_f32 v9, v4, v5
	v_and_b32_e32 v5, 0xffff0000, v10
	v_lshlrev_b32_e32 v4, 16, v10
	v_pk_mul_f32 v[4:5], v[16:17], v[4:5]
	s_nop 0
	v_cvt_pk_bf16_f32 v10, v4, v5
	v_and_b32_e32 v5, 0xffff0000, v11
	v_lshlrev_b32_e32 v4, 16, v11
	v_pk_mul_f32 v[4:5], v[18:19], v[4:5]
	s_nop 0
	v_cvt_pk_bf16_f32 v11, v4, v5
	v_lshl_add_u64 v[4:5], v[6:7], 0, v[22:23]
	global_store_dwordx4 v[4:5], v[8:11], off
	v_add_u32_e32 v4, s38, v3
	v_ashrrev_i32_e32 v5, 31, v4
	v_lshlrev_b64 v[8:9], 10, v[4:5]
	global_load_dwordx4 v[4:7], v[58:59], off offset:288
	v_or3_b32 v8, v8, s0, v2
	v_lshlrev_b64 v[22:23], 1, v[8:9]
	s_waitcnt vmcnt(0) lgkmcnt(0)
	v_lshl_add_u64 v[4:5], v[4:5], 0, v[22:23]
	global_load_dwordx4 v[8:11], v[4:5], off
	v_mad_u64_u32 v[4:5], s[34:35], v3, s23, v[0:1]
	ds_read_b128 v[12:15], v4
	ds_read_b128 v[16:19], v4 offset:16
	v_add_u32_e32 v3, 0x300, v20
	s_waitcnt vmcnt(0) lgkmcnt(0)
	v_and_b32_e32 v5, 0xffff0000, v8
	v_lshlrev_b32_e32 v4, 16, v8
	v_pk_mul_f32 v[4:5], v[12:13], v[4:5]
	s_nop 0
	v_cvt_pk_bf16_f32 v8, v4, v5
	v_and_b32_e32 v5, 0xffff0000, v9
	v_lshlrev_b32_e32 v4, 16, v9
	v_pk_mul_f32 v[4:5], v[14:15], v[4:5]
	s_nop 0
	v_cvt_pk_bf16_f32 v9, v4, v5
	v_and_b32_e32 v5, 0xffff0000, v10
	v_lshlrev_b32_e32 v4, 16, v10
	v_pk_mul_f32 v[4:5], v[16:17], v[4:5]
	s_nop 0
	v_cvt_pk_bf16_f32 v10, v4, v5
	v_and_b32_e32 v5, 0xffff0000, v11
	v_lshlrev_b32_e32 v4, 16, v11
	v_pk_mul_f32 v[4:5], v[18:19], v[4:5]
	s_nop 0
	v_cvt_pk_bf16_f32 v11, v4, v5
	v_lshl_add_u64 v[4:5], v[6:7], 0, v[22:23]
	global_store_dwordx4 v[4:5], v[8:11], off
	s_nop 1
	v_ashrrev_i32_e32 v10, 3, v3
	v_add_u32_e32 v4, s38, v10
	v_ashrrev_i32_e32 v5, 31, v4
	v_lshlrev_b64 v[6:7], 10, v[4:5]
	v_or3_b32 v6, v6, s0, v2
	global_load_dwordx4 v[2:5], v[58:59], off offset:288
	v_lshlrev_b64 v[18:19], 1, v[6:7]
	s_waitcnt vmcnt(0) lgkmcnt(0)
	v_lshl_add_u64 v[2:3], v[2:3], 0, v[18:19]
	global_load_dwordx4 v[6:9], v[2:3], off
	v_mad_u64_u32 v[2:3], s[0:1], v10, s23, v[0:1]
	ds_read_b128 v[10:13], v2
	ds_read_b128 v[14:17], v2 offset:16
	v_readlane_b32 s0, v254, 45
	s_add_i32 s19, s19, s0
	s_cmp_ge_i32 s9, s8
	s_waitcnt vmcnt(0) lgkmcnt(0)
	v_and_b32_e32 v3, 0xffff0000, v6
	v_lshlrev_b32_e32 v2, 16, v6
	v_pk_mul_f32 v[2:3], v[10:11], v[2:3]
	s_nop 0
	v_cvt_pk_bf16_f32 v6, v2, v3
	v_and_b32_e32 v3, 0xffff0000, v7
	v_lshlrev_b32_e32 v2, 16, v7
	v_pk_mul_f32 v[2:3], v[12:13], v[2:3]
	s_nop 0
	v_cvt_pk_bf16_f32 v7, v2, v3
	v_and_b32_e32 v3, 0xffff0000, v8
	v_lshlrev_b32_e32 v2, 16, v8
	v_pk_mul_f32 v[2:3], v[14:15], v[2:3]
	s_nop 0
	v_cvt_pk_bf16_f32 v8, v2, v3
	v_and_b32_e32 v3, 0xffff0000, v9
	v_lshlrev_b32_e32 v2, 16, v9
	v_pk_mul_f32 v[2:3], v[16:17], v[2:3]
	s_nop 0
	v_cvt_pk_bf16_f32 v9, v2, v3
	v_lshl_add_u64 v[2:3], v[4:5], 0, v[18:19]
	global_store_dwordx4 v[2:3], v[6:9], off
	s_cbranch_scc1 .LBB0_605

; template <int NT, bool BKN, bool MASK = false, bool ROWSS = false, class Epi> ...
;     ...
; #pragma unroll
;   for (int i = 0; i < 4; ++i) {
;     const int row = (t >> 3) + 32 * i;
;     const bool v = MASK ? (row < mvalid) : true;
;     amask |= v ? (1u << i) : 0u;
;     int r = v ? row : 0;
;     if (arows) r = arows[r];
;     ap[i] = A + (size_t)r * lda + (t & 7) * 8;
;   }
; #pragma unroll
;   for (int i = 0; i < NT; ++i) {
;     if (!BKN) bp[i] = B + (size_t)((t >> 3) + 32 * i) * ldb + (t & 7) * 8;
;     else { const int c = t + 256 * i; bp[i] = B + (size_t)(c / CPR) * ldb + (c % CPR) * 8; }
;   }
;   const size_t bstep = BKN ? (size_t)64 * ldb : (size_t)64;
;   int nmi = 4;
;   if (MASK) { nmi = (mvalid - wr * 64 + 15) >> 4; nmi = nmi < 0 ? 0 : (nmi > 4 ? 4 : nmi); nmi = __builtin_amdgcn_readfirstlane(nmi); }
;   u32x4 ra0[4], rb0[NT], ra1[4], rb1[NT];
;     ...
;   GEMM_LOAD(ra0, rb0, 0);
;   GEMM_LOAD(ra1, rb1, 1);
;   GEMM_STORE(ra0, rb0, 0);
;   GEMM_LOAD(ra0, rb0, (2 < nkm1 ? 2 : nkm1));
;   __syncthreads();
.LBB0_1278:
	s_and_b64 vcc, exec, s[36:37]
	s_cbranch_vccz .LBB0_1659
	v_mov_b32_e32 v85, v187
	s_waitcnt lgkmcnt(0)
	v_ashrrev_i32_e32 v2, 3, v85
	v_lshlrev_b32_e32 v12, 4, v85
	v_ashrrev_i32_e32 v3, 31, v2
	v_and_b32_e32 v0, 0x70, v12
	v_lshlrev_b64 v[2:3], 10, v[2:3]
	v_lshl_add_u64 v[4:5], v[168:169], 0, v[0:1]
	v_lshl_add_u64 v[6:7], v[2:3], 0, s[10:11]
	v_lshl_add_u64 v[8:9], v[2:3], 0, s[12:13]
	v_lshl_add_u64 v[10:11], v[2:3], 0, s[26:27]
	v_lshl_add_u64 v[66:67], v[4:5], 0, v[2:3]
	v_lshl_add_u64 v[68:69], v[4:5], 0, v[6:7]
	v_lshl_add_u64 v[70:71], v[4:5], 0, v[8:9]
	v_lshl_add_u64 v[72:73], v[4:5], 0, v[10:11]
	v_lshl_add_u64 v[4:5], v[166:167], 0, v[0:1]
	v_lshl_add_u64 v[74:75], v[4:5], 0, v[2:3]
	v_lshl_add_u64 v[76:77], v[4:5], 0, v[6:7]
	v_lshl_add_u64 v[78:79], v[4:5], 0, v[8:9]
	v_lshl_add_u64 v[80:81], v[4:5], 0, v[10:11]
	s_barrier
	global_load_dwordx4 v[34:37], v[66:67], off
	global_load_dwordx4 v[38:41], v[74:75], off
	global_load_dwordx4 v[42:45], v[68:69], off
	global_load_dwordx4 v[46:49], v[70:71], off
	global_load_dwordx4 v[50:53], v[72:73], off
	global_load_dwordx4 v[54:57], v[76:77], off
	global_load_dwordx4 v[58:61], v[78:79], off
	global_load_dwordx4 v[62:65], v[80:81], off
	v_lshrrev_b32_e32 v2, 4, v85
	v_bfe_u32 v86, v85, 1, 3
	v_xor_b32_e32 v3, v2, v85
	v_and_b32_e32 v4, 0xffffff80, v12
	v_bitop3_b32 v2, v2, v86, 3 bitop3:0x6c
	v_lshlrev_b32_e32 v3, 4, v3
	v_lshlrev_b32_e32 v89, 4, v2
	v_and_or_b32 v87, v3, s14, v4
	global_load_dwordx4 v[90:93], v[66:67], off offset:128
	global_load_dwordx4 v[94:97], v[74:75], off offset:128
	global_load_dwordx4 v[2:5], v[66:67], off offset:256
	global_load_dwordx4 v[6:9], v[74:75], off offset:256
	global_load_dwordx4 v[98:101], v[70:71], off offset:128
	global_load_dwordx4 v[102:105], v[78:79], off offset:128
	global_load_dwordx4 v[106:109], v[68:69], off offset:128
	global_load_dwordx4 v[10:13], v[68:69], off offset:256
	global_load_dwordx4 v[14:17], v[70:71], off offset:256
	global_load_dwordx4 v[110:113], v[72:73], off offset:128
	global_load_dwordx4 v[18:21], v[72:73], off offset:256
	global_load_dwordx4 v[114:117], v[76:77], off offset:128
	global_load_dwordx4 v[22:25], v[76:77], off offset:256
	global_load_dwordx4 v[26:29], v[78:79], off offset:256
	global_load_dwordx4 v[118:121], v[80:81], off offset:128
	global_load_dwordx4 v[30:33], v[80:81], off offset:256
	v_and_b32_e32 v82, 15, v85
	v_ashrrev_i32_e32 v0, 7, v85
	v_lshlrev_b32_e32 v88, 7, v82
	v_lshl_or_b32 v158, v0, 13, v88
	v_or_b32_e32 v84, v89, v158
	v_bfe_u32 v83, v85, 6, 1
	v_bfe_u32 v85, v85, 4, 2
	v_lshl_or_b32 v159, v83, 13, v88
	v_bitop3_b32 v86, v85, v86, 4 bitop3:0x36
	v_or_b32_e32 v88, v89, v159
	v_lshlrev_b32_e32 v89, 4, v86
	v_or_b32_e32 v86, v89, v158
	v_or_b32_e32 v89, v89, v159
	v_lshlrev_b32_e32 v0, 6, v0
	s_waitcnt vmcnt(0) lgkmcnt(0)
	ds_write_b128 v87, v[34:37]
	ds_write_b128 v87, v[38:41] offset:16384
	ds_write_b128 v87, v[42:45] offset:4096
	ds_write_b128 v87, v[46:49] offset:8192
	ds_write_b128 v87, v[50:53] offset:12288
	ds_write_b128 v87, v[54:57] offset:20480
	ds_write_b128 v87, v[58:61] offset:24576
	ds_write_b128 v87, v[62:65] offset:28672
	s_waitcnt lgkmcnt(0)
	s_barrier
	ds_read_b128 v[34:37], v84
	ds_read_b128 v[122:125], v84 offset:2048
	ds_read_b128 v[138:141], v84 offset:4096
	ds_read_b128 v[154:157], v84 offset:6144
	ds_read_b128 v[38:41], v88 offset:16384
	ds_read_b128 v[46:49], v88 offset:18432
	ds_read_b128 v[54:57], v88 offset:20480
	ds_read_b128 v[62:65], v88 offset:22528
	ds_read_b128 v[166:169], v86
	ds_read_b128 v[188:191], v86 offset:6144
	s_waitcnt lgkmcnt(5)
	v_mfma_f32_16x16x32_bf16 v[42:45], v[34:37], v[38:41], 0
	ds_read_b128 v[182:185], v89 offset:22528
	s_waitcnt lgkmcnt(5)
	v_mfma_f32_16x16x32_bf16 v[50:53], v[34:37], v[46:49], 0
	s_waitcnt lgkmcnt(4)
	v_mfma_f32_16x16x32_bf16 v[58:61], v[34:37], v[54:57], 0
	s_waitcnt lgkmcnt(3)
	v_mfma_f32_16x16x32_bf16 v[34:37], v[34:37], v[62:65], 0
	v_mfma_f32_16x16x32_bf16 v[126:129], v[122:125], v[38:41], 0
	v_mfma_f32_16x16x32_bf16 v[130:133], v[122:125], v[46:49], 0
	v_mfma_f32_16x16x32_bf16 v[134:137], v[122:125], v[54:57], 0
	v_mfma_f32_16x16x32_bf16 v[122:125], v[122:125], v[62:65], 0
	v_mfma_f32_16x16x32_bf16 v[142:145], v[138:141], v[38:41], 0
	v_mfma_f32_16x16x32_bf16 v[146:149], v[138:141], v[46:49], 0
	v_mfma_f32_16x16x32_bf16 v[150:153], v[138:141], v[54:57], 0
	v_mfma_f32_16x16x32_bf16 v[138:141], v[138:141], v[62:65], 0
	v_mfma_f32_16x16x32_bf16 v[38:41], v[154:157], v[38:41], 0
	v_mfma_f32_16x16x32_bf16 v[46:49], v[154:157], v[46:49], 0
	v_mfma_f32_16x16x32_bf16 v[54:57], v[154:157], v[54:57], 0
	v_mfma_f32_16x16x32_bf16 v[154:157], v[154:157], v[62:65], 0
	ds_read_b128 v[62:65], v89 offset:16384
	s_waitcnt lgkmcnt(0)
	v_mfma_f32_16x16x32_bf16 v[170:173], v[166:169], v[62:65], v[42:45]
	s_nop 2
	ds_read_b128 v[42:45], v89 offset:18432
	s_waitcnt lgkmcnt(0)
	v_mfma_f32_16x16x32_bf16 v[174:177], v[166:169], v[42:45], v[50:53]
	s_nop 2
	ds_read_b128 v[50:53], v89 offset:20480
	s_waitcnt lgkmcnt(0)
	v_mfma_f32_16x16x32_bf16 v[178:181], v[166:169], v[50:53], v[58:61]
	v_mfma_f32_16x16x32_bf16 v[166:169], v[166:169], v[182:185], v[34:37]
	s_nop 2
	ds_read_b128 v[34:37], v86 offset:2048
	s_waitcnt lgkmcnt(0)
	v_mfma_f32_16x16x32_bf16 v[126:129], v[34:37], v[62:65], v[126:129]
	v_mfma_f32_16x16x32_bf16 v[130:133], v[34:37], v[42:45], v[130:133]
	v_mfma_f32_16x16x32_bf16 v[134:137], v[34:37], v[50:53], v[134:137]
	v_mfma_f32_16x16x32_bf16 v[122:125], v[34:37], v[182:185], v[122:125]
	ds_read_b128 v[34:37], v86 offset:4096
	ds_write_b128 v87, v[90:93] offset:32768
	ds_write_b128 v87, v[106:109] offset:36864
	ds_write_b128 v87, v[98:101] offset:40960
	ds_write_b128 v87, v[110:113] offset:45056
	ds_write_b128 v87, v[94:97] offset:49152
	ds_write_b128 v87, v[114:117] offset:53248
	ds_write_b128 v87, v[102:105] offset:57344
	ds_write_b128 v87, v[118:121] offset:61440
	s_waitcnt lgkmcnt(8)
	v_mfma_f32_16x16x32_bf16 v[142:145], v[34:37], v[62:65], v[142:145]
	v_mfma_f32_16x16x32_bf16 v[146:149], v[34:37], v[42:45], v[146:149]
	v_mfma_f32_16x16x32_bf16 v[150:153], v[34:37], v[50:53], v[150:153]
	v_mfma_f32_16x16x32_bf16 v[138:141], v[34:37], v[182:185], v[138:141]
	v_mfma_f32_16x16x32_bf16 v[192:195], v[188:191], v[62:65], v[38:41]
	v_mfma_f32_16x16x32_bf16 v[196:199], v[188:191], v[42:45], v[46:49]
	v_mfma_f32_16x16x32_bf16 v[200:203], v[188:191], v[50:53], v[54:57]
	global_load_dwordx4 v[34:37], v[66:67], off offset:384
	global_load_dwordx4 v[38:41], v[68:69], off offset:384
	global_load_dwordx4 v[42:45], v[70:71], off offset:384
	global_load_dwordx4 v[46:49], v[72:73], off offset:384
	global_load_dwordx4 v[50:53], v[74:75], off offset:384
	global_load_dwordx4 v[54:57], v[76:77], off offset:384
	global_load_dwordx4 v[58:61], v[78:79], off offset:384
	global_load_dwordx4 v[62:65], v[80:81], off offset:384
	s_waitcnt lgkmcnt(0)
	s_barrier
; template <int NT, bool BKN, bool MASK = false, bool ROWSS = false, class Epi> ...
;     ...
;   for (int kt = 0; kt < nk - 2; kt += 2) {
;     GEMM_COMPUTE(0);
;     GEMM_STORE(ra1, rb1, 1);
;     GEMM_LOAD(ra1, rb1, kt + 3);
;     __syncthreads();
;     GEMM_COMPUTE(1);
;     GEMM_STORE(ra0, rb0, 0);
;     GEMM_LOAD(ra0, rb0, (kt + 4 < nkm1 ? kt + 4 : nkm1));
;     __syncthreads();
;   }
	ds_read_b128 v[90:93], v84 offset:32768
	ds_read_b128 v[98:101], v88 offset:49152
	v_mfma_f32_16x16x32_bf16 v[94:97], v[188:191], v[182:185], v[154:157]
	ds_read_b128 v[106:109], v88 offset:51200
	ds_read_b128 v[114:117], v88 offset:53248
	s_nop 0
	ds_read_b128 v[154:157], v88 offset:55296
	s_waitcnt lgkmcnt(0)
	v_mfma_f32_16x16x32_bf16 v[102:105], v[90:93], v[98:101], v[170:173]
	s_nop 2
	ds_read_b128 v[170:173], v86 offset:32768
	v_mfma_f32_16x16x32_bf16 v[110:113], v[90:93], v[106:109], v[174:177]
	v_mfma_f32_16x16x32_bf16 v[118:121], v[90:93], v[114:117], v[178:181]
	s_nop 1
	ds_read_b128 v[174:177], v89 offset:53248
	v_mfma_f32_16x16x32_bf16 v[90:93], v[90:93], v[154:157], v[166:169]
	ds_read_b128 v[178:181], v89 offset:55296
	s_nop 1
	ds_read_b128 v[166:169], v84 offset:34816
	s_waitcnt lgkmcnt(0)
	v_mfma_f32_16x16x32_bf16 v[126:129], v[166:169], v[98:101], v[126:129]
	v_mfma_f32_16x16x32_bf16 v[130:133], v[166:169], v[106:109], v[130:133]
	v_mfma_f32_16x16x32_bf16 v[134:137], v[166:169], v[114:117], v[134:137]
	v_mfma_f32_16x16x32_bf16 v[122:125], v[166:169], v[154:157], v[122:125]
	ds_read_b128 v[166:169], v84 offset:36864
	s_waitcnt lgkmcnt(0)
	v_mfma_f32_16x16x32_bf16 v[142:145], v[166:169], v[98:101], v[142:145]
	v_mfma_f32_16x16x32_bf16 v[146:149], v[166:169], v[106:109], v[146:149]
	v_mfma_f32_16x16x32_bf16 v[150:153], v[166:169], v[114:117], v[150:153]
	v_mfma_f32_16x16x32_bf16 v[138:141], v[166:169], v[154:157], v[138:141]
	ds_read_b128 v[166:169], v84 offset:38912
	s_waitcnt lgkmcnt(0)
	v_mfma_f32_16x16x32_bf16 v[98:101], v[166:169], v[98:101], v[192:195]
	v_mfma_f32_16x16x32_bf16 v[106:109], v[166:169], v[106:109], v[196:199]
	v_mfma_f32_16x16x32_bf16 v[114:117], v[166:169], v[114:117], v[200:203]
	v_mfma_f32_16x16x32_bf16 v[94:97], v[166:169], v[154:157], v[94:97]
	ds_read_b128 v[154:157], v89 offset:49152
	ds_read_b128 v[166:169], v89 offset:51200
	s_waitcnt lgkmcnt(0)
	v_mfma_f32_16x16x32_bf16 v[102:105], v[170:173], v[154:157], v[102:105]
	v_mfma_f32_16x16x32_bf16 v[110:113], v[170:173], v[166:169], v[110:113]
	v_mfma_f32_16x16x32_bf16 v[118:121], v[170:173], v[174:177], v[118:121]
	v_mfma_f32_16x16x32_bf16 v[90:93], v[170:173], v[178:181], v[90:93]
	ds_read_b128 v[170:173], v86 offset:34816
	s_waitcnt lgkmcnt(0)
	v_mfma_f32_16x16x32_bf16 v[126:129], v[170:173], v[154:157], v[126:129]
	v_mfma_f32_16x16x32_bf16 v[130:133], v[170:173], v[166:169], v[130:133]
	v_mfma_f32_16x16x32_bf16 v[134:137], v[170:173], v[174:177], v[134:137]
	v_mfma_f32_16x16x32_bf16 v[122:125], v[170:173], v[178:181], v[122:125]
	ds_read_b128 v[170:173], v86 offset:36864
	s_waitcnt lgkmcnt(0)
	v_mfma_f32_16x16x32_bf16 v[142:145], v[170:173], v[154:157], v[142:145]
	v_mfma_f32_16x16x32_bf16 v[146:149], v[170:173], v[166:169], v[146:149]
	v_mfma_f32_16x16x32_bf16 v[150:153], v[170:173], v[174:177], v[150:153]
	v_mfma_f32_16x16x32_bf16 v[138:141], v[170:173], v[178:181], v[138:141]
	ds_read_b128 v[170:173], v86 offset:38912
	ds_write_b128 v87, v[2:5]
	ds_write_b128 v87, v[10:13] offset:4096
	ds_write_b128 v87, v[14:17] offset:8192
	ds_write_b128 v87, v[18:21] offset:12288
	ds_write_b128 v87, v[6:9] offset:16384
	ds_write_b128 v87, v[22:25] offset:20480
	ds_write_b128 v87, v[26:29] offset:24576
	ds_write_b128 v87, v[30:33] offset:28672
	global_load_dwordx4 v[2:5], v[66:67], off offset:512
	global_load_dwordx4 v[6:9], v[68:69], off offset:512
	global_load_dwordx4 v[10:13], v[70:71], off offset:512
	global_load_dwordx4 v[14:17], v[72:73], off offset:512
	global_load_dwordx4 v[18:21], v[74:75], off offset:512
	global_load_dwordx4 v[22:25], v[76:77], off offset:512
	global_load_dwordx4 v[26:29], v[78:79], off offset:512
	global_load_dwordx4 v[30:33], v[80:81], off offset:512
	s_waitcnt lgkmcnt(0)
	v_mfma_f32_16x16x32_bf16 v[98:101], v[170:173], v[154:157], v[98:101]
	s_barrier
	ds_read_b128 v[154:157], v84
	v_mfma_f32_16x16x32_bf16 v[106:109], v[170:173], v[166:169], v[106:109]
	ds_read_b128 v[166:169], v88 offset:16384
	v_mfma_f32_16x16x32_bf16 v[114:117], v[170:173], v[174:177], v[114:117]
	ds_read_b128 v[174:177], v88 offset:20480
	v_mfma_f32_16x16x32_bf16 v[94:97], v[170:173], v[178:181], v[94:97]
	ds_read_b128 v[170:173], v88 offset:18432
	ds_read_b128 v[178:181], v88 offset:22528
	s_waitcnt lgkmcnt(0)
	v_mfma_f32_16x16x32_bf16 v[102:105], v[154:157], v[166:169], v[102:105]
	v_mfma_f32_16x16x32_bf16 v[110:113], v[154:157], v[170:173], v[110:113]
	v_mfma_f32_16x16x32_bf16 v[118:121], v[154:157], v[174:177], v[118:121]
	v_mfma_f32_16x16x32_bf16 v[90:93], v[154:157], v[178:181], v[90:93]
	ds_read_b128 v[154:157], v84 offset:2048
	s_waitcnt lgkmcnt(0)
	v_mfma_f32_16x16x32_bf16 v[126:129], v[154:157], v[166:169], v[126:129]
	v_mfma_f32_16x16x32_bf16 v[130:133], v[154:157], v[170:173], v[130:133]
	v_mfma_f32_16x16x32_bf16 v[134:137], v[154:157], v[174:177], v[134:137]
	v_mfma_f32_16x16x32_bf16 v[122:125], v[154:157], v[178:181], v[122:125]
	ds_read_b128 v[154:157], v84 offset:4096
	s_waitcnt lgkmcnt(0)
	v_mfma_f32_16x16x32_bf16 v[142:145], v[154:157], v[166:169], v[142:145]
	v_mfma_f32_16x16x32_bf16 v[146:149], v[154:157], v[170:173], v[146:149]
	v_mfma_f32_16x16x32_bf16 v[150:153], v[154:157], v[174:177], v[150:153]
	v_mfma_f32_16x16x32_bf16 v[138:141], v[154:157], v[178:181], v[138:141]
	ds_read_b128 v[154:157], v84 offset:6144
	s_waitcnt lgkmcnt(0)
	v_mfma_f32_16x16x32_bf16 v[98:101], v[154:157], v[166:169], v[98:101]
	ds_read_b128 v[166:169], v86
	v_mfma_f32_16x16x32_bf16 v[106:109], v[154:157], v[170:173], v[106:109]
	ds_read_b128 v[170:173], v89 offset:18432
	v_mfma_f32_16x16x32_bf16 v[114:117], v[154:157], v[174:177], v[114:117]
	ds_read_b128 v[174:177], v89 offset:20480
	v_mfma_f32_16x16x32_bf16 v[94:97], v[154:157], v[178:181], v[94:97]
	ds_read_b128 v[154:157], v89 offset:16384
	ds_read_b128 v[178:181], v89 offset:22528
	s_waitcnt lgkmcnt(0)
; template <int NT, bool BKN, bool MASK = false, bool ROWSS = false, class Epi> ...
;     ...
;   for (int kt = 0; kt < nk - 2; kt += 2) {
;     GEMM_COMPUTE(0);
;     GEMM_STORE(ra1, rb1, 1);
;     GEMM_LOAD(ra1, rb1, kt + 3);
;     __syncthreads();
;     GEMM_COMPUTE(1);
;     GEMM_STORE(ra0, rb0, 0);
;     GEMM_LOAD(ra0, rb0, (kt + 4 < nkm1 ? kt + 4 : nkm1));
;     __syncthreads();
;   }
	v_mfma_f32_16x16x32_bf16 v[102:105], v[166:169], v[154:157], v[102:105]
	v_mfma_f32_16x16x32_bf16 v[110:113], v[166:169], v[170:173], v[110:113]
	v_mfma_f32_16x16x32_bf16 v[118:121], v[166:169], v[174:177], v[118:121]
	v_mfma_f32_16x16x32_bf16 v[90:93], v[166:169], v[178:181], v[90:93]
	ds_read_b128 v[166:169], v86 offset:2048
	s_waitcnt lgkmcnt(0)
	v_mfma_f32_16x16x32_bf16 v[126:129], v[166:169], v[154:157], v[126:129]
	v_mfma_f32_16x16x32_bf16 v[130:133], v[166:169], v[170:173], v[130:133]
	v_mfma_f32_16x16x32_bf16 v[134:137], v[166:169], v[174:177], v[134:137]
	v_mfma_f32_16x16x32_bf16 v[122:125], v[166:169], v[178:181], v[122:125]
	ds_read_b128 v[166:169], v86 offset:4096
	s_waitcnt lgkmcnt(0)
	v_mfma_f32_16x16x32_bf16 v[142:145], v[166:169], v[154:157], v[142:145]
	v_mfma_f32_16x16x32_bf16 v[146:149], v[166:169], v[170:173], v[146:149]
	v_mfma_f32_16x16x32_bf16 v[150:153], v[166:169], v[174:177], v[150:153]
	v_mfma_f32_16x16x32_bf16 v[138:141], v[166:169], v[178:181], v[138:141]
	ds_read_b128 v[166:169], v86 offset:6144
	s_waitcnt vmcnt(0)
	ds_write_b128 v87, v[34:37] offset:32768
	ds_write_b128 v87, v[38:41] offset:36864
	ds_write_b128 v87, v[42:45] offset:40960
	ds_write_b128 v87, v[46:49] offset:45056
	ds_write_b128 v87, v[50:53] offset:49152
	ds_write_b128 v87, v[54:57] offset:53248
	ds_write_b128 v87, v[58:61] offset:57344
	ds_write_b128 v87, v[62:65] offset:61440
	global_load_dwordx4 v[34:37], v[66:67], off offset:640
	global_load_dwordx4 v[38:41], v[68:69], off offset:640
	global_load_dwordx4 v[42:45], v[70:71], off offset:640
	global_load_dwordx4 v[46:49], v[72:73], off offset:640
	global_load_dwordx4 v[50:53], v[74:75], off offset:640
	global_load_dwordx4 v[54:57], v[76:77], off offset:640
	global_load_dwordx4 v[58:61], v[78:79], off offset:640
	global_load_dwordx4 v[62:65], v[80:81], off offset:640
	s_waitcnt lgkmcnt(0)
	v_mfma_f32_16x16x32_bf16 v[98:101], v[166:169], v[154:157], v[98:101]
	s_barrier
	ds_read_b128 v[154:157], v84 offset:32768
	v_mfma_f32_16x16x32_bf16 v[106:109], v[166:169], v[170:173], v[106:109]
	ds_read_b128 v[170:173], v88 offset:51200
	v_mfma_f32_16x16x32_bf16 v[114:117], v[166:169], v[174:177], v[114:117]
	ds_read_b128 v[174:177], v88 offset:53248
	v_mfma_f32_16x16x32_bf16 v[94:97], v[166:169], v[178:181], v[94:97]
	ds_read_b128 v[166:169], v88 offset:49152
	ds_read_b128 v[178:181], v88 offset:55296
	s_waitcnt lgkmcnt(0)
	v_mfma_f32_16x16x32_bf16 v[102:105], v[154:157], v[166:169], v[102:105]
	v_mfma_f32_16x16x32_bf16 v[110:113], v[154:157], v[170:173], v[110:113]
	v_mfma_f32_16x16x32_bf16 v[118:121], v[154:157], v[174:177], v[118:121]
	v_mfma_f32_16x16x32_bf16 v[90:93], v[154:157], v[178:181], v[90:93]
	ds_read_b128 v[154:157], v84 offset:34816
	s_waitcnt lgkmcnt(0)
	v_mfma_f32_16x16x32_bf16 v[126:129], v[154:157], v[166:169], v[126:129]
	v_mfma_f32_16x16x32_bf16 v[130:133], v[154:157], v[170:173], v[130:133]
	v_mfma_f32_16x16x32_bf16 v[134:137], v[154:157], v[174:177], v[134:137]
	v_mfma_f32_16x16x32_bf16 v[122:125], v[154:157], v[178:181], v[122:125]
	ds_read_b128 v[154:157], v84 offset:36864
	s_waitcnt lgkmcnt(0)
	v_mfma_f32_16x16x32_bf16 v[142:145], v[154:157], v[166:169], v[142:145]
	v_mfma_f32_16x16x32_bf16 v[146:149], v[154:157], v[170:173], v[146:149]
	v_mfma_f32_16x16x32_bf16 v[150:153], v[154:157], v[174:177], v[150:153]
	v_mfma_f32_16x16x32_bf16 v[138:141], v[154:157], v[178:181], v[138:141]
	ds_read_b128 v[154:157], v84 offset:38912
	s_waitcnt lgkmcnt(0)
	v_mfma_f32_16x16x32_bf16 v[98:101], v[154:157], v[166:169], v[98:101]
	ds_read_b128 v[166:169], v86 offset:32768
	v_mfma_f32_16x16x32_bf16 v[106:109], v[154:157], v[170:173], v[106:109]
	ds_read_b128 v[170:173], v89 offset:51200
	v_mfma_f32_16x16x32_bf16 v[114:117], v[154:157], v[174:177], v[114:117]
	ds_read_b128 v[174:177], v89 offset:53248
	v_mfma_f32_16x16x32_bf16 v[94:97], v[154:157], v[178:181], v[94:97]
	ds_read_b128 v[154:157], v89 offset:49152
	ds_read_b128 v[178:181], v89 offset:55296
	s_waitcnt lgkmcnt(0)
	v_mfma_f32_16x16x32_bf16 v[102:105], v[166:169], v[154:157], v[102:105]
	v_mfma_f32_16x16x32_bf16 v[110:113], v[166:169], v[170:173], v[110:113]
	v_mfma_f32_16x16x32_bf16 v[118:121], v[166:169], v[174:177], v[118:121]
	v_mfma_f32_16x16x32_bf16 v[90:93], v[166:169], v[178:181], v[90:93]
	ds_read_b128 v[166:169], v86 offset:34816
	s_waitcnt lgkmcnt(0)
	v_mfma_f32_16x16x32_bf16 v[126:129], v[166:169], v[154:157], v[126:129]
	v_mfma_f32_16x16x32_bf16 v[130:133], v[166:169], v[170:173], v[130:133]
	v_mfma_f32_16x16x32_bf16 v[134:137], v[166:169], v[174:177], v[134:137]
	v_mfma_f32_16x16x32_bf16 v[122:125], v[166:169], v[178:181], v[122:125]
	ds_read_b128 v[166:169], v86 offset:36864
	s_waitcnt lgkmcnt(0)
	v_mfma_f32_16x16x32_bf16 v[142:145], v[166:169], v[154:157], v[142:145]
	v_mfma_f32_16x16x32_bf16 v[146:149], v[166:169], v[170:173], v[146:149]
	v_mfma_f32_16x16x32_bf16 v[150:153], v[166:169], v[174:177], v[150:153]
	v_mfma_f32_16x16x32_bf16 v[138:141], v[166:169], v[178:181], v[138:141]
	ds_read_b128 v[166:169], v86 offset:38912
	ds_write_b128 v87, v[2:5]
	ds_write_b128 v87, v[6:9] offset:4096
	ds_write_b128 v87, v[10:13] offset:8192
	ds_write_b128 v87, v[14:17] offset:12288
	ds_write_b128 v87, v[18:21] offset:16384
	ds_write_b128 v87, v[22:25] offset:20480
	ds_write_b128 v87, v[26:29] offset:24576
	ds_write_b128 v87, v[30:33] offset:28672
	global_load_dwordx4 v[2:5], v[66:67], off offset:768
	global_load_dwordx4 v[6:9], v[68:69], off offset:768
	global_load_dwordx4 v[10:13], v[70:71], off offset:768
	global_load_dwordx4 v[14:17], v[72:73], off offset:768
	global_load_dwordx4 v[18:21], v[74:75], off offset:768
	global_load_dwordx4 v[22:25], v[76:77], off offset:768
	global_load_dwordx4 v[26:29], v[78:79], off offset:768
	global_load_dwordx4 v[30:33], v[80:81], off offset:768
	s_waitcnt lgkmcnt(0)
	v_mfma_f32_16x16x32_bf16 v[98:101], v[166:169], v[154:157], v[98:101]
	s_barrier
; template <int NT, bool BKN, bool MASK = false, bool ROWSS = false, class Epi> ...
;     ...
;   for (int kt = 0; kt < nk - 2; kt += 2) {
;     GEMM_COMPUTE(0);
;     GEMM_STORE(ra1, rb1, 1);
;     GEMM_LOAD(ra1, rb1, kt + 3);
;     __syncthreads();
;     GEMM_COMPUTE(1);
;     GEMM_STORE(ra0, rb0, 0);
;     GEMM_LOAD(ra0, rb0, (kt + 4 < nkm1 ? kt + 4 : nkm1));
;     __syncthreads();
;   }
;   GEMM_COMPUTE(0);
;   GEMM_STORE(ra1, rb1, 1);
;   __syncthreads();
	ds_read_b128 v[154:157], v84
	v_mfma_f32_16x16x32_bf16 v[106:109], v[166:169], v[170:173], v[106:109]
	ds_read_b128 v[170:173], v88 offset:18432
	v_mfma_f32_16x16x32_bf16 v[114:117], v[166:169], v[174:177], v[114:117]
	ds_read_b128 v[174:177], v88 offset:20480
	v_mfma_f32_16x16x32_bf16 v[94:97], v[166:169], v[178:181], v[94:97]
	ds_read_b128 v[166:169], v88 offset:16384
	ds_read_b128 v[178:181], v88 offset:22528
	s_waitcnt lgkmcnt(0)
	v_mfma_f32_16x16x32_bf16 v[102:105], v[154:157], v[166:169], v[102:105]
	v_mfma_f32_16x16x32_bf16 v[110:113], v[154:157], v[170:173], v[110:113]
	v_mfma_f32_16x16x32_bf16 v[118:121], v[154:157], v[174:177], v[118:121]
	v_mfma_f32_16x16x32_bf16 v[90:93], v[154:157], v[178:181], v[90:93]
	ds_read_b128 v[154:157], v84 offset:2048
	s_waitcnt lgkmcnt(0)
	v_mfma_f32_16x16x32_bf16 v[126:129], v[154:157], v[166:169], v[126:129]
	v_mfma_f32_16x16x32_bf16 v[130:133], v[154:157], v[170:173], v[130:133]
	v_mfma_f32_16x16x32_bf16 v[134:137], v[154:157], v[174:177], v[134:137]
	v_mfma_f32_16x16x32_bf16 v[122:125], v[154:157], v[178:181], v[122:125]
	ds_read_b128 v[154:157], v84 offset:4096
	s_waitcnt lgkmcnt(0)
	v_mfma_f32_16x16x32_bf16 v[142:145], v[154:157], v[166:169], v[142:145]
	v_mfma_f32_16x16x32_bf16 v[146:149], v[154:157], v[170:173], v[146:149]
	v_mfma_f32_16x16x32_bf16 v[150:153], v[154:157], v[174:177], v[150:153]
	v_mfma_f32_16x16x32_bf16 v[138:141], v[154:157], v[178:181], v[138:141]
	ds_read_b128 v[154:157], v84 offset:6144
	s_waitcnt lgkmcnt(0)
	v_mfma_f32_16x16x32_bf16 v[98:101], v[154:157], v[166:169], v[98:101]
	ds_read_b128 v[166:169], v86
	v_mfma_f32_16x16x32_bf16 v[106:109], v[154:157], v[170:173], v[106:109]
	ds_read_b128 v[170:173], v89 offset:18432
	v_mfma_f32_16x16x32_bf16 v[114:117], v[154:157], v[174:177], v[114:117]
	ds_read_b128 v[174:177], v89 offset:20480
	v_mfma_f32_16x16x32_bf16 v[94:97], v[154:157], v[178:181], v[94:97]
	ds_read_b128 v[154:157], v89 offset:16384
	ds_read_b128 v[178:181], v89 offset:22528
	s_waitcnt lgkmcnt(0)
	v_mfma_f32_16x16x32_bf16 v[102:105], v[166:169], v[154:157], v[102:105]
	v_mfma_f32_16x16x32_bf16 v[110:113], v[166:169], v[170:173], v[110:113]
	v_mfma_f32_16x16x32_bf16 v[118:121], v[166:169], v[174:177], v[118:121]
	v_mfma_f32_16x16x32_bf16 v[90:93], v[166:169], v[178:181], v[90:93]
	ds_read_b128 v[166:169], v86 offset:2048
	s_waitcnt lgkmcnt(0)
	v_mfma_f32_16x16x32_bf16 v[126:129], v[166:169], v[154:157], v[126:129]
	v_mfma_f32_16x16x32_bf16 v[130:133], v[166:169], v[170:173], v[130:133]
	v_mfma_f32_16x16x32_bf16 v[134:137], v[166:169], v[174:177], v[134:137]
	v_mfma_f32_16x16x32_bf16 v[122:125], v[166:169], v[178:181], v[122:125]
	ds_read_b128 v[166:169], v86 offset:4096
	s_waitcnt lgkmcnt(0)
	v_mfma_f32_16x16x32_bf16 v[142:145], v[166:169], v[154:157], v[142:145]
	v_mfma_f32_16x16x32_bf16 v[146:149], v[166:169], v[170:173], v[146:149]
	v_mfma_f32_16x16x32_bf16 v[150:153], v[166:169], v[174:177], v[150:153]
	v_mfma_f32_16x16x32_bf16 v[138:141], v[166:169], v[178:181], v[138:141]
	ds_read_b128 v[166:169], v86 offset:6144
	s_waitcnt vmcnt(0)
	ds_write_b128 v87, v[34:37] offset:32768
	ds_write_b128 v87, v[38:41] offset:36864
	ds_write_b128 v87, v[42:45] offset:40960
	ds_write_b128 v87, v[46:49] offset:45056
	ds_write_b128 v87, v[50:53] offset:49152
	ds_write_b128 v87, v[54:57] offset:53248
	ds_write_b128 v87, v[58:61] offset:57344
	ds_write_b128 v87, v[62:65] offset:61440
	global_load_dwordx4 v[34:37], v[66:67], off offset:896
	global_load_dwordx4 v[38:41], v[68:69], off offset:896
	global_load_dwordx4 v[42:45], v[70:71], off offset:896
	global_load_dwordx4 v[46:49], v[72:73], off offset:896
	global_load_dwordx4 v[50:53], v[74:75], off offset:896
	global_load_dwordx4 v[54:57], v[76:77], off offset:896
	global_load_dwordx4 v[58:61], v[78:79], off offset:896
	global_load_dwordx4 v[62:65], v[80:81], off offset:896
	s_waitcnt lgkmcnt(0)
	s_barrier
	ds_read_b128 v[66:69], v84 offset:32768
	ds_read_b128 v[74:77], v88 offset:49152
	v_mfma_f32_16x16x32_bf16 v[70:73], v[166:169], v[178:181], v[94:97]
	s_nop 2
	ds_read_b128 v[94:97], v88 offset:51200
	v_mfma_f32_16x16x32_bf16 v[98:101], v[166:169], v[154:157], v[98:101]
	ds_read_b128 v[154:157], v88 offset:55296
	s_waitcnt lgkmcnt(0)
	v_mfma_f32_16x16x32_bf16 v[78:81], v[66:69], v[74:77], v[102:105]
	v_mfma_f32_16x16x32_bf16 v[102:105], v[66:69], v[94:97], v[110:113]
	s_nop 2
	ds_read_b128 v[110:113], v88 offset:53248
	s_waitcnt lgkmcnt(0)
	v_mfma_f32_16x16x32_bf16 v[118:121], v[66:69], v[110:113], v[118:121]
	v_mfma_f32_16x16x32_bf16 v[66:69], v[66:69], v[154:157], v[90:93]
	s_nop 2
	ds_read_b128 v[90:93], v84 offset:34816
	s_waitcnt lgkmcnt(0)
	v_mfma_f32_16x16x32_bf16 v[126:129], v[90:93], v[74:77], v[126:129]
	v_mfma_f32_16x16x32_bf16 v[130:133], v[90:93], v[94:97], v[130:133]
	v_mfma_f32_16x16x32_bf16 v[134:137], v[90:93], v[110:113], v[134:137]
	v_mfma_f32_16x16x32_bf16 v[90:93], v[90:93], v[154:157], v[122:125]
	s_nop 2
	ds_read_b128 v[122:125], v84 offset:36864
	s_waitcnt lgkmcnt(0)
	v_mfma_f32_16x16x32_bf16 v[142:145], v[122:125], v[74:77], v[142:145]
	v_mfma_f32_16x16x32_bf16 v[146:149], v[122:125], v[94:97], v[146:149]
	v_mfma_f32_16x16x32_bf16 v[150:153], v[122:125], v[110:113], v[150:153]
	v_mfma_f32_16x16x32_bf16 v[122:125], v[122:125], v[154:157], v[138:141]
	s_nop 2
	ds_read_b128 v[138:141], v84 offset:38912
	v_mfma_f32_16x16x32_bf16 v[106:109], v[166:169], v[170:173], v[106:109]
	v_mfma_f32_16x16x32_bf16 v[114:117], v[166:169], v[174:177], v[114:117]
	s_waitcnt lgkmcnt(0)
; template <int NT, bool BKN, bool MASK = false, bool ROWSS = false, class Epi> ...
;     ...
;   GEMM_COMPUTE(0);
;   GEMM_STORE(ra1, rb1, 1);
;   __syncthreads();
;   GEMM_COMPUTE(1);
	v_mfma_f32_16x16x32_bf16 v[94:97], v[138:141], v[94:97], v[106:109]
	s_nop 4
	ds_read_b128 v[106:109], v86 offset:32768
	v_mfma_f32_16x16x32_bf16 v[74:77], v[138:141], v[74:77], v[98:101]
	v_mfma_f32_16x16x32_bf16 v[98:101], v[138:141], v[110:113], v[114:117]
	ds_read_b128 v[110:113], v89 offset:49152
	v_mfma_f32_16x16x32_bf16 v[70:73], v[138:141], v[154:157], v[70:73]
	s_nop 0
	ds_read_b128 v[114:117], v89 offset:51200
	ds_read_b128 v[138:141], v89 offset:53248
	ds_read_b128 v[154:157], v89 offset:55296
	s_waitcnt lgkmcnt(0)
	v_mfma_f32_16x16x32_bf16 v[78:81], v[106:109], v[110:113], v[78:81]
	v_mfma_f32_16x16x32_bf16 v[102:105], v[106:109], v[114:117], v[102:105]
	v_mfma_f32_16x16x32_bf16 v[118:121], v[106:109], v[138:141], v[118:121]
	v_mfma_f32_16x16x32_bf16 v[66:69], v[106:109], v[154:157], v[66:69]
	ds_read_b128 v[106:109], v86 offset:34816
	s_waitcnt lgkmcnt(0)
	v_mfma_f32_16x16x32_bf16 v[126:129], v[106:109], v[110:113], v[126:129]
	v_mfma_f32_16x16x32_bf16 v[130:133], v[106:109], v[114:117], v[130:133]
	v_mfma_f32_16x16x32_bf16 v[134:137], v[106:109], v[138:141], v[134:137]
	v_mfma_f32_16x16x32_bf16 v[90:93], v[106:109], v[154:157], v[90:93]
	ds_read_b128 v[106:109], v86 offset:36864
	s_waitcnt lgkmcnt(0)
	v_mfma_f32_16x16x32_bf16 v[142:145], v[106:109], v[110:113], v[142:145]
	v_mfma_f32_16x16x32_bf16 v[146:149], v[106:109], v[114:117], v[146:149]
	v_mfma_f32_16x16x32_bf16 v[150:153], v[106:109], v[138:141], v[150:153]
	v_mfma_f32_16x16x32_bf16 v[106:109], v[106:109], v[154:157], v[122:125]
	s_nop 2
	ds_read_b128 v[122:125], v86 offset:38912
	ds_write_b128 v87, v[2:5]
	ds_write_b128 v87, v[6:9] offset:4096
	ds_write_b128 v87, v[10:13] offset:8192
	ds_write_b128 v87, v[14:17] offset:12288
	ds_write_b128 v87, v[18:21] offset:16384
	ds_write_b128 v87, v[22:25] offset:20480
	ds_write_b128 v87, v[26:29] offset:24576
	ds_write_b128 v87, v[30:33] offset:28672
	s_waitcnt lgkmcnt(0)
	s_barrier
	ds_read_b128 v[2:5], v84
	ds_read_b128 v[10:13], v88 offset:16384
	v_mfma_f32_16x16x32_bf16 v[6:9], v[122:125], v[154:157], v[70:73]
	ds_read_b128 v[18:21], v88 offset:18432
	ds_read_b128 v[26:29], v88 offset:20480
	s_nop 0
	ds_read_b128 v[70:73], v88 offset:22528
	s_waitcnt lgkmcnt(0)
	v_mfma_f32_16x16x32_bf16 v[14:17], v[2:5], v[10:13], v[78:81]
	v_mfma_f32_16x16x32_bf16 v[22:25], v[2:5], v[18:21], v[102:105]
	v_mfma_f32_16x16x32_bf16 v[30:33], v[2:5], v[26:29], v[118:121]
	v_mfma_f32_16x16x32_bf16 v[2:5], v[2:5], v[70:73], v[66:69]
	s_nop 2
	ds_read_b128 v[66:69], v84 offset:2048
	v_mfma_f32_16x16x32_bf16 v[74:77], v[122:125], v[110:113], v[74:77]
	s_waitcnt lgkmcnt(0)
	v_mfma_f32_16x16x32_bf16 v[78:81], v[66:69], v[10:13], v[126:129]
	v_mfma_f32_16x16x32_bf16 v[102:105], v[66:69], v[18:21], v[130:133]
	v_mfma_f32_16x16x32_bf16 v[110:113], v[66:69], v[26:29], v[134:137]
	v_mfma_f32_16x16x32_bf16 v[66:69], v[66:69], v[70:73], v[90:93]
	s_nop 2
	ds_read_b128 v[90:93], v84 offset:4096
	v_mfma_f32_16x16x32_bf16 v[94:97], v[122:125], v[114:117], v[94:97]
	v_mfma_f32_16x16x32_bf16 v[98:101], v[122:125], v[138:141], v[98:101]
	s_waitcnt lgkmcnt(0)
	v_mfma_f32_16x16x32_bf16 v[114:117], v[90:93], v[10:13], v[142:145]
	v_mfma_f32_16x16x32_bf16 v[118:121], v[90:93], v[18:21], v[146:149]
	v_mfma_f32_16x16x32_bf16 v[122:125], v[90:93], v[26:29], v[150:153]
	v_mfma_f32_16x16x32_bf16 v[90:93], v[90:93], v[70:73], v[106:109]
	s_nop 2
	ds_read_b128 v[106:109], v84 offset:6144
	s_waitcnt lgkmcnt(0)
	v_mfma_f32_16x16x32_bf16 v[10:13], v[106:109], v[10:13], v[74:77]
	s_nop 2
	ds_read_b128 v[74:77], v86
	v_mfma_f32_16x16x32_bf16 v[18:21], v[106:109], v[18:21], v[94:97]
	v_mfma_f32_16x16x32_bf16 v[26:29], v[106:109], v[26:29], v[98:101]
	s_nop 1
	ds_read_b128 v[94:97], v89 offset:18432
	ds_read_b128 v[98:101], v89 offset:20480
	v_mfma_f32_16x16x32_bf16 v[6:9], v[106:109], v[70:73], v[6:9]
	ds_read_b128 v[70:73], v89 offset:16384
	ds_read_b128 v[106:109], v89 offset:22528
	s_waitcnt lgkmcnt(0)
	v_mfma_f32_16x16x32_bf16 v[14:17], v[74:77], v[70:73], v[14:17]
	v_mfma_f32_16x16x32_bf16 v[22:25], v[74:77], v[94:97], v[22:25]
	v_mfma_f32_16x16x32_bf16 v[30:33], v[74:77], v[98:101], v[30:33]
	v_mfma_f32_16x16x32_bf16 v[2:5], v[74:77], v[106:109], v[2:5]
	ds_read_b128 v[74:77], v86 offset:2048
	s_waitcnt lgkmcnt(0)
	v_mfma_f32_16x16x32_bf16 v[78:81], v[74:77], v[70:73], v[78:81]
	v_mfma_f32_16x16x32_bf16 v[102:105], v[74:77], v[94:97], v[102:105]
	v_mfma_f32_16x16x32_bf16 v[110:113], v[74:77], v[98:101], v[110:113]
	v_mfma_f32_16x16x32_bf16 v[66:69], v[74:77], v[106:109], v[66:69]
	ds_read_b128 v[74:77], v86 offset:4096
	s_waitcnt lgkmcnt(0)
	v_mfma_f32_16x16x32_bf16 v[114:117], v[74:77], v[70:73], v[114:117]
	v_mfma_f32_16x16x32_bf16 v[118:121], v[74:77], v[94:97], v[118:121]
	v_mfma_f32_16x16x32_bf16 v[122:125], v[74:77], v[98:101], v[122:125]
	v_mfma_f32_16x16x32_bf16 v[74:77], v[74:77], v[106:109], v[90:93]
	s_nop 2
	ds_read_b128 v[90:93], v86 offset:6144
	s_waitcnt vmcnt(0)
	ds_write_b128 v87, v[34:37] offset:32768
	ds_write_b128 v87, v[38:41] offset:36864
	ds_write_b128 v87, v[42:45] offset:40960
	ds_write_b128 v87, v[46:49] offset:45056
	ds_write_b128 v87, v[50:53] offset:49152
	ds_write_b128 v87, v[54:57] offset:53248
	ds_write_b128 v87, v[58:61] offset:57344
	ds_write_b128 v87, v[62:65] offset:61440
	s_waitcnt lgkmcnt(0)
	s_barrier
; __device__ __forceinline__ u16 f2bf(float f) { return (u16)(pack2(f, 0.f) & 0xffffu); }
; template <int NT, class VF, class RP>
; __device__ __forceinline__ void epi_staged_bf16(f32x4 (&acc)[4][NT], int r0, int c0, unsigned char* smem, VF vf, RP rowptr) {
;     ...
;   __syncthreads();
; #pragma unroll
;   for (int mi = 0; mi < 4; ++mi)
; #pragma unroll
;     for (int ni = 0; ni < NT; ++ni)
; #pragma unroll
;       for (int j = 0; j < 4; ++j) {
;         const int r = r0 + mi * 16 + j, c = c0 + ni * 16;
;         Ts[r * PITCH + c] = f2bf(vf(r, c, acc[mi][ni][j]));
;       }
; __device__ __forceinline__ void phase_moe_down(const Params& p, int l, bool last, unsigned char* smem) {
;     ...
;     auto epi = [&](f32x4(&acc)[4][4], int r0, int c0) {
;       auto vf = [&](int r, int, float v) { return (r < mvalid ? gate[r] : 0.f) * v; };
;       auto rp = [&](int r) -> u16* { return r < mvalid ? yb + (size_t)r * 1024 : nullptr; };
;       epi_staged_bf16<4>(acc, r0, c0, smem, vf, rp);
	ds_read_b128 v[34:37], v84 offset:32768
	ds_read_b128 v[54:57], v84 offset:36864
	ds_read_b128 v[38:41], v88 offset:49152
	ds_read_b128 v[42:45], v88 offset:51200
	ds_read_b128 v[46:49], v88 offset:53248
	ds_read_b128 v[50:53], v88 offset:55296
	s_waitcnt lgkmcnt(3)
	v_mfma_f32_16x16x32_bf16 v[14:17], v[34:37], v[38:41], v[14:17]
	s_waitcnt lgkmcnt(2)
	v_mfma_f32_16x16x32_bf16 v[22:25], v[34:37], v[42:45], v[22:25]
	s_waitcnt lgkmcnt(1)
	v_mfma_f32_16x16x32_bf16 v[30:33], v[34:37], v[46:49], v[30:33]
	s_waitcnt lgkmcnt(0)
	v_mfma_f32_16x16x32_bf16 v[2:5], v[34:37], v[50:53], v[2:5]
	ds_read_b128 v[34:37], v84 offset:34816
	v_mfma_f32_16x16x32_bf16 v[10:13], v[90:93], v[70:73], v[10:13]
	v_mfma_f32_16x16x32_bf16 v[18:21], v[90:93], v[94:97], v[18:21]
	v_mfma_f32_16x16x32_bf16 v[26:29], v[90:93], v[98:101], v[26:29]
	v_mfma_f32_16x16x32_bf16 v[6:9], v[90:93], v[106:109], v[6:9]
	v_mfma_f32_16x16x32_bf16 v[94:97], v[54:57], v[42:45], v[118:121]
	v_mfma_f32_16x16x32_bf16 v[98:101], v[54:57], v[46:49], v[122:125]
	s_nop 1
	ds_read_b128 v[118:121], v89 offset:53248
	s_waitcnt lgkmcnt(1)
	v_mfma_f32_16x16x32_bf16 v[70:73], v[34:37], v[38:41], v[78:81]
	ds_read_b128 v[122:125], v89 offset:55296
	v_mfma_f32_16x16x32_bf16 v[78:81], v[34:37], v[42:45], v[102:105]
	v_mfma_f32_16x16x32_bf16 v[90:93], v[34:37], v[46:49], v[110:113]
	v_mfma_f32_16x16x32_bf16 v[34:37], v[34:37], v[50:53], v[66:69]
	v_mfma_f32_16x16x32_bf16 v[66:69], v[54:57], v[38:41], v[114:117]
	v_mfma_f32_16x16x32_bf16 v[74:77], v[54:57], v[50:53], v[74:77]
	ds_read_b128 v[54:57], v84 offset:38912
	s_nop 0
	ds_read_b128 v[114:117], v89 offset:51200
	s_waitcnt lgkmcnt(1)
	v_mfma_f32_16x16x32_bf16 v[102:105], v[54:57], v[42:45], v[18:21]
	s_nop 2
	ds_read_b128 v[18:21], v86 offset:32768
	v_mfma_f32_16x16x32_bf16 v[110:113], v[54:57], v[50:53], v[6:9]
	s_nop 2
	ds_read_b128 v[6:9], v89 offset:49152
	s_waitcnt lgkmcnt(1)
	v_mfma_f32_16x16x32_bf16 v[50:53], v[18:21], v[122:125], v[2:5]
	s_nop 2
	ds_read_b128 v[2:5], v86 offset:34816
	v_mfma_f32_16x16x32_bf16 v[10:13], v[54:57], v[38:41], v[10:13]
	v_mfma_f32_16x16x32_bf16 v[106:109], v[54:57], v[46:49], v[26:29]
	s_waitcnt lgkmcnt(0)
	v_mfma_f32_16x16x32_bf16 v[46:49], v[2:5], v[6:9], v[70:73]
	v_mfma_f32_16x16x32_bf16 v[42:45], v[2:5], v[114:117], v[78:81]
	s_nop 1
	v_mov_b32_e32 v70, 0
	v_mfma_f32_16x16x32_bf16 v[38:41], v[2:5], v[118:121], v[90:93]
	v_mfma_f32_16x16x32_bf16 v[34:37], v[2:5], v[122:125], v[34:37]
	ds_read_b128 v[2:5], v86 offset:36864
	v_mfma_f32_16x16x32_bf16 v[62:65], v[18:21], v[6:9], v[14:17]
	v_mfma_f32_16x16x32_bf16 v[58:61], v[18:21], v[114:117], v[22:25]
	v_mfma_f32_16x16x32_bf16 v[54:57], v[18:21], v[118:121], v[30:33]
	s_waitcnt lgkmcnt(0)
	v_mfma_f32_16x16x32_bf16 v[30:33], v[2:5], v[6:9], v[66:69]
	v_mfma_f32_16x16x32_bf16 v[26:29], v[2:5], v[114:117], v[94:97]
	s_nop 1
	v_lshl_or_b32 v66, v85, 2, v0
	v_mov_b32_e32 v0, v187
	v_cmp_gt_i32_e32 vcc, s60, v66
	v_mfma_f32_16x16x32_bf16 v[22:25], v[2:5], v[118:121], v[98:101]
	v_ashrrev_i32_e32 v67, 31, v66
	v_mov_b32_e32 v69, 0
	v_mfma_f32_16x16x32_bf16 v[18:21], v[2:5], v[122:125], v[74:77]
	ds_read_b128 v[2:5], v86 offset:38912
	s_waitcnt lgkmcnt(0)
	v_mfma_f32_16x16x32_bf16 v[14:17], v[2:5], v[6:9], v[10:13]
	s_barrier
	v_lshl_add_u64 v[230:231], v[66:67], 2, v[162:163]
	global_load_dwordx4 v[204:207], v[230:231], off offset:0
	global_load_dwordx4 v[208:211], v[230:231], off offset:64
	global_load_dwordx4 v[216:219], v[230:231], off offset:128
	global_load_dwordx4 v[220:223], v[230:231], off offset:192
	v_mfma_f32_16x16x32_bf16 v[10:13], v[2:5], v[114:117], v[102:105]
	v_mfma_f32_16x16x32_bf16 v[6:9], v[2:5], v[118:121], v[106:109]
	v_mfma_f32_16x16x32_bf16 v[2:5], v[2:5], v[122:125], v[110:113]
	s_waitcnt vmcnt(0)
	s_and_saveexec_b64 s[0:1], vcc
	s_cbranch_execz .LBB0_1281
	v_lshl_add_u64 v[68:69], v[66:67], 2, v[162:163]
	v_mov_b32_e32 v69, v204
.LBB0_1281:
	s_or_b64 exec, exec, s[0:1]
	v_lshl_or_b32 v68, v83, 6, v82
	s_waitcnt lgkmcnt(0)
	v_mul_f32_e32 v62, v62, v69
	v_mul_lo_u32 v69, v66, s22
	v_lshlrev_b32_e32 v71, 1, v68
	v_cvt_pk_bf16_f32 v62, v62, s0
	v_lshl_add_u32 v71, v69, 1, v71
	ds_write_b16 v71, v62
	v_or_b32_e32 v62, 1, v66
	v_cmp_gt_i32_e64 s[38:39], s60, v62
	v_mov_b32_e32 v71, 0
	s_and_saveexec_b64 s[0:1], s[38:39]
	s_cbranch_execz .LBB0_1283
	v_lshl_add_u64 v[72:73], v[66:67], 2, v[162:163]
	v_mov_b32_e32 v71, v205
.LBB0_1283:
	s_or_b64 exec, exec, s[0:1]
	s_waitcnt lgkmcnt(0)
	v_mul_f32_e32 v63, v63, v71
	v_cvt_pk_bf16_f32 v71, v63, s0
	v_mul_lo_u32 v63, v62, s23
	v_lshl_add_u32 v62, v68, 1, v63
	ds_write_b16 v62, v71
	v_or_b32_e32 v71, 2, v66
	v_cmp_gt_i32_e64 s[40:41], s60, v71
	s_and_saveexec_b64 s[0:1], s[40:41]
	s_cbranch_execz .LBB0_1285
	v_lshl_add_u64 v[70:71], v[66:67], 2, v[162:163]
	v_mov_b32_e32 v70, v206
.LBB0_1285:
	s_or_b64 exec, exec, s[0:1]
	s_waitcnt lgkmcnt(0)
	v_mul_f32_e32 v64, v64, v70
	v_add_u32_e32 v63, 0x110, v63
	v_cvt_pk_bf16_f32 v64, v64, s0
	v_lshl_add_u32 v63, v68, 1, v63
	ds_write_b16 v63, v64
	v_or_b32_e32 v64, 3, v66
	v_cmp_gt_i32_e64 s[42:43], s60, v64
	v_mov_b32_e32 v64, 0
	v_mov_b32_e32 v70, 0
	s_and_saveexec_b64 s[0:1], s[42:43]
	s_cbranch_execz .LBB0_1287
	v_lshl_add_u64 v[70:71], v[66:67], 2, v[162:163]
	v_mov_b32_e32 v70, v207
.LBB0_1287:
	s_or_b64 exec, exec, s[0:1]
	s_waitcnt lgkmcnt(0)
	v_mul_f32_e32 v65, v65, v70
	v_cvt_pk_bf16_f32 v65, v65, s0
	ds_write_b16 v63, v65 offset:272
	s_and_saveexec_b64 s[0:1], vcc
	s_cbranch_execz .LBB0_1289
	v_lshl_add_u64 v[64:65], v[66:67], 2, v[162:163]
	v_mov_b32_e32 v64, v204
; __device__ __forceinline__ u16 f2bf(float f) { return (u16)(pack2(f, 0.f) & 0xffffu); }
; template <int NT, class VF, class RP>
; __device__ __forceinline__ void epi_staged_bf16(f32x4 (&acc)[4][NT], int r0, int c0, unsigned char* smem, VF vf, RP rowptr) {
;     ...
;   __syncthreads();
; #pragma unroll
;   for (int mi = 0; mi < 4; ++mi)
; #pragma unroll
;     for (int ni = 0; ni < NT; ++ni)
; #pragma unroll
;       for (int j = 0; j < 4; ++j) {
;         const int r = r0 + mi * 16 + j, c = c0 + ni * 16;
;         Ts[r * PITCH + c] = f2bf(vf(r, c, acc[mi][ni][j]));
;       }
; __device__ __forceinline__ void phase_moe_down(const Params& p, int l, bool last, unsigned char* smem) {
;     ...
;     auto epi = [&](f32x4(&acc)[4][4], int r0, int c0) {
;       auto vf = [&](int r, int, float v) { return (r < mvalid ? gate[r] : 0.f) * v; };
;       auto rp = [&](int r) -> u16* { return r < mvalid ? yb + (size_t)r * 1024 : nullptr; };
;       epi_staged_bf16<4>(acc, r0, c0, smem, vf, rp);
.LBB0_1289:
	s_or_b64 exec, exec, s[0:1]
	s_waitcnt lgkmcnt(0)
	v_mul_f32_e32 v58, v58, v64
	v_lshlrev_b32_e32 v64, 1, v69
	v_cvt_pk_bf16_f32 v58, v58, s0
	v_lshl_add_u32 v64, v68, 1, v64
	ds_write_b16 v64, v58 offset:32
	v_mov_b32_e32 v58, 0
	v_mov_b32_e32 v65, 0
	s_and_saveexec_b64 s[0:1], s[38:39]
	s_cbranch_execz .LBB0_1291
	v_lshl_add_u64 v[70:71], v[66:67], 2, v[162:163]
	v_mov_b32_e32 v65, v205
.LBB0_1291:
	s_or_b64 exec, exec, s[0:1]
	s_waitcnt lgkmcnt(0)
	v_mul_f32_e32 v59, v59, v65
	v_cvt_pk_bf16_f32 v59, v59, s0
	ds_write_b16 v62, v59 offset:32
	s_and_saveexec_b64 s[0:1], s[40:41]
	s_cbranch_execz .LBB0_1293
	v_lshl_add_u64 v[58:59], v[66:67], 2, v[162:163]
	v_mov_b32_e32 v58, v206
.LBB0_1293:
	s_or_b64 exec, exec, s[0:1]
	s_waitcnt lgkmcnt(0)
	v_mul_f32_e32 v58, v60, v58
	v_cvt_pk_bf16_f32 v58, v58, s0
	v_mov_b32_e32 v59, 0
	v_mov_b32_e32 v60, 0
	ds_write_b16 v63, v58 offset:32
	s_and_saveexec_b64 s[0:1], s[42:43]
	s_cbranch_execz .LBB0_1295
	v_lshl_add_u64 v[70:71], v[66:67], 2, v[162:163]
	v_mov_b32_e32 v60, v207
.LBB0_1295:
	s_or_b64 exec, exec, s[0:1]
	s_waitcnt lgkmcnt(0)
	v_mul_f32_e32 v60, v61, v60
	v_add_u32_e32 v58, 0x110, v63
	v_cvt_pk_bf16_f32 v60, v60, s0
	ds_write_b16 v58, v60 offset:32
	s_and_saveexec_b64 s[0:1], vcc
	s_cbranch_execz .LBB0_1297
	v_lshl_add_u64 v[60:61], v[66:67], 2, v[162:163]
	v_mov_b32_e32 v59, v204
.LBB0_1297:
	s_or_b64 exec, exec, s[0:1]
	s_waitcnt lgkmcnt(0)
	v_mul_f32_e32 v54, v54, v59
	v_cvt_pk_bf16_f32 v54, v54, s0
	ds_write_b16 v64, v54 offset:64
	v_mov_b32_e32 v54, 0
	v_mov_b32_e32 v59, 0
	s_and_saveexec_b64 s[0:1], s[38:39]
	s_cbranch_execz .LBB0_1299
	v_lshl_add_u64 v[60:61], v[66:67], 2, v[162:163]
	v_mov_b32_e32 v59, v205
.LBB0_1299:
	s_or_b64 exec, exec, s[0:1]
	s_waitcnt lgkmcnt(0)
	v_mul_f32_e32 v55, v55, v59
	v_cvt_pk_bf16_f32 v55, v55, s0
	ds_write_b16 v62, v55 offset:64
	s_and_saveexec_b64 s[0:1], s[40:41]
	s_cbranch_execz .LBB0_1301
	v_lshl_add_u64 v[54:55], v[66:67], 2, v[162:163]
	v_mov_b32_e32 v54, v206
.LBB0_1301:
	s_or_b64 exec, exec, s[0:1]
	s_waitcnt lgkmcnt(0)
	v_mul_f32_e32 v54, v56, v54
	v_cvt_pk_bf16_f32 v54, v54, s0
	ds_write_b16 v63, v54 offset:64
	v_mov_b32_e32 v54, 0
	v_mov_b32_e32 v55, 0
	s_and_saveexec_b64 s[0:1], s[42:43]
	s_cbranch_execz .LBB0_1303
	v_lshl_add_u64 v[60:61], v[66:67], 2, v[162:163]
	v_mov_b32_e32 v55, v207
.LBB0_1303:
	s_or_b64 exec, exec, s[0:1]
	s_waitcnt lgkmcnt(0)
	v_mul_f32_e32 v55, v57, v55
	v_cvt_pk_bf16_f32 v55, v55, s0
	ds_write_b16 v58, v55 offset:64
	s_and_saveexec_b64 s[0:1], vcc
	s_cbranch_execz .LBB0_1305
	v_lshl_add_u64 v[54:55], v[66:67], 2, v[162:163]
	v_mov_b32_e32 v54, v204
.LBB0_1305:
	s_or_b64 exec, exec, s[0:1]
	s_waitcnt lgkmcnt(0)
	v_mul_f32_e32 v50, v50, v54
	v_cvt_pk_bf16_f32 v50, v50, s0
	ds_write_b16 v64, v50 offset:96
	v_mov_b32_e32 v50, 0
	v_mov_b32_e32 v54, 0
	s_and_saveexec_b64 s[0:1], s[38:39]
	s_cbranch_execz .LBB0_1307
	v_lshl_add_u64 v[54:55], v[66:67], 2, v[162:163]
	v_mov_b32_e32 v54, v205
.LBB0_1307:
	s_or_b64 exec, exec, s[0:1]
	s_waitcnt lgkmcnt(0)
	v_mul_f32_e32 v51, v51, v54
	v_cvt_pk_bf16_f32 v51, v51, s0
	ds_write_b16 v62, v51 offset:96
	s_and_saveexec_b64 s[0:1], s[40:41]
	s_cbranch_execz .LBB0_1309
	v_lshl_add_u64 v[50:51], v[66:67], 2, v[162:163]
	v_mov_b32_e32 v50, v206
.LBB0_1309:
	s_or_b64 exec, exec, s[0:1]
	s_waitcnt lgkmcnt(0)
	v_mul_f32_e32 v50, v52, v50
	v_cvt_pk_bf16_f32 v50, v50, s0
	ds_write_b16 v63, v50 offset:96
	v_mov_b32_e32 v50, 0
	v_mov_b32_e32 v51, 0
	s_and_saveexec_b64 s[0:1], s[42:43]
	s_cbranch_execz .LBB0_1311
	v_lshl_add_u64 v[54:55], v[66:67], 2, v[162:163]
	v_mov_b32_e32 v51, v207
.LBB0_1311:
	s_or_b64 exec, exec, s[0:1]
	s_waitcnt lgkmcnt(0)
	v_mul_f32_e32 v51, v53, v51
	v_cvt_pk_bf16_f32 v51, v51, s0
	ds_write_b16 v58, v51 offset:96
	v_or_b32_e32 v51, 16, v66
	v_cmp_gt_i32_e32 vcc, s60, v51
	s_and_saveexec_b64 s[0:1], vcc
	s_cbranch_execz .LBB0_1313
	v_lshl_add_u64 v[52:53], v[66:67], 2, v[162:163]
	v_mov_b32_e32 v50, v208
.LBB0_1313:
	s_or_b64 exec, exec, s[0:1]
	s_waitcnt lgkmcnt(0)
	v_mul_f32_e32 v46, v46, v50
	v_mul_lo_u32 v51, v51, s23
	v_cvt_pk_bf16_f32 v50, v46, s0
	v_lshl_add_u32 v46, v68, 1, v51
	ds_write_b16 v46, v50
	v_or_b32_e32 v50, 17, v66
	v_cmp_gt_i32_e64 s[38:39], s60, v50
	v_mov_b32_e32 v50, 0
	v_mov_b32_e32 v52, 0
	s_and_saveexec_b64 s[0:1], s[38:39]
	s_cbranch_execz .LBB0_1315
	v_lshl_add_u64 v[52:53], v[66:67], 2, v[162:163]
	v_mov_b32_e32 v52, v209
.LBB0_1315:
	s_or_b64 exec, exec, s[0:1]
	s_waitcnt lgkmcnt(0)
	v_mul_f32_e32 v47, v47, v52
	v_add_u32_e32 v51, 0x110, v51
	v_cvt_pk_bf16_f32 v52, v47, s0
	v_lshl_add_u32 v47, v68, 1, v51
	ds_write_b16 v47, v52
	v_or_b32_e32 v52, 18, v66
	v_cmp_gt_i32_e64 s[40:41], s60, v52
	s_and_saveexec_b64 s[0:1], s[40:41]
	s_cbranch_execz .LBB0_1317
	v_lshl_add_u64 v[52:53], v[66:67], 2, v[162:163]
	v_mov_b32_e32 v50, v210
.LBB0_1317:
	s_or_b64 exec, exec, s[0:1]
	s_waitcnt lgkmcnt(0)
	v_mul_f32_e32 v48, v48, v50
	v_cvt_pk_bf16_f32 v50, v48, s0
	v_add_u32_e32 v48, 0x110, v51
	v_lshl_add_u32 v48, v68, 1, v48
	ds_write_b16 v48, v50
	v_or_b32_e32 v50, 19, v66
	v_cmp_gt_i32_e64 s[42:43], s60, v50
	v_mov_b32_e32 v50, 0
	v_mov_b32_e32 v51, 0
	s_and_saveexec_b64 s[0:1], s[42:43]
	s_cbranch_execz .LBB0_1319
	v_lshl_add_u64 v[52:53], v[66:67], 2, v[162:163]
	v_mov_b32_e32 v51, v211
.LBB0_1319:
	s_or_b64 exec, exec, s[0:1]
	s_waitcnt lgkmcnt(0)
	v_mul_f32_e32 v49, v49, v51
	v_cvt_pk_bf16_f32 v49, v49, s0
	ds_write_b16 v48, v49 offset:272
	s_and_saveexec_b64 s[0:1], vcc
	s_cbranch_execz .LBB0_1321
	v_lshl_add_u64 v[50:51], v[66:67], 2, v[162:163]
	v_mov_b32_e32 v50, v208
; __device__ __forceinline__ u16 f2bf(float f) { return (u16)(pack2(f, 0.f) & 0xffffu); }
; template <int NT, class VF, class RP>
; __device__ __forceinline__ void epi_staged_bf16(f32x4 (&acc)[4][NT], int r0, int c0, unsigned char* smem, VF vf, RP rowptr) {
;     ...
;   __syncthreads();
; #pragma unroll
;   for (int mi = 0; mi < 4; ++mi)
; #pragma unroll
;     for (int ni = 0; ni < NT; ++ni)
; #pragma unroll
;       for (int j = 0; j < 4; ++j) {
;         const int r = r0 + mi * 16 + j, c = c0 + ni * 16;
;         Ts[r * PITCH + c] = f2bf(vf(r, c, acc[mi][ni][j]));
;       }
; __device__ __forceinline__ void phase_moe_down(const Params& p, int l, bool last, unsigned char* smem) {
;     ...
;     auto epi = [&](f32x4(&acc)[4][4], int r0, int c0) {
;       auto vf = [&](int r, int, float v) { return (r < mvalid ? gate[r] : 0.f) * v; };
;       auto rp = [&](int r) -> u16* { return r < mvalid ? yb + (size_t)r * 1024 : nullptr; };
;       epi_staged_bf16<4>(acc, r0, c0, smem, vf, rp);
.LBB0_1321:
	s_or_b64 exec, exec, s[0:1]
	s_waitcnt lgkmcnt(0)
	v_mul_f32_e32 v42, v42, v50
	v_cvt_pk_bf16_f32 v42, v42, s0
	ds_write_b16 v46, v42 offset:32
	v_mov_b32_e32 v42, 0
	v_mov_b32_e32 v49, 0
	s_and_saveexec_b64 s[0:1], s[38:39]
	s_cbranch_execz .LBB0_1323
	v_lshl_add_u64 v[50:51], v[66:67], 2, v[162:163]
	v_mov_b32_e32 v49, v209
.LBB0_1323:
	s_or_b64 exec, exec, s[0:1]
	s_waitcnt lgkmcnt(0)
	v_mul_f32_e32 v43, v43, v49
	v_cvt_pk_bf16_f32 v43, v43, s0
	ds_write_b16 v47, v43 offset:32
	s_and_saveexec_b64 s[0:1], s[40:41]
	s_cbranch_execz .LBB0_1325
	v_lshl_add_u64 v[42:43], v[66:67], 2, v[162:163]
	v_mov_b32_e32 v42, v210
.LBB0_1325:
	s_or_b64 exec, exec, s[0:1]
	s_waitcnt lgkmcnt(0)
	v_mul_f32_e32 v42, v44, v42
	v_cvt_pk_bf16_f32 v42, v42, s0
	v_mov_b32_e32 v43, 0
	v_mov_b32_e32 v44, 0
	ds_write_b16 v48, v42 offset:32
	s_and_saveexec_b64 s[0:1], s[42:43]
	s_cbranch_execz .LBB0_1327
	v_lshl_add_u64 v[50:51], v[66:67], 2, v[162:163]
	v_mov_b32_e32 v44, v211
.LBB0_1327:
	s_or_b64 exec, exec, s[0:1]
	s_waitcnt lgkmcnt(0)
	v_mul_f32_e32 v44, v45, v44
	v_add_u32_e32 v42, 0x110, v48
	v_cvt_pk_bf16_f32 v44, v44, s0
	ds_write_b16 v42, v44 offset:32
	s_and_saveexec_b64 s[0:1], vcc
	s_cbranch_execz .LBB0_1329
	v_lshl_add_u64 v[44:45], v[66:67], 2, v[162:163]
	v_mov_b32_e32 v43, v208
.LBB0_1329:
	s_or_b64 exec, exec, s[0:1]
	s_waitcnt lgkmcnt(0)
	v_mul_f32_e32 v38, v38, v43
	v_cvt_pk_bf16_f32 v38, v38, s0
	ds_write_b16 v46, v38 offset:64
	v_mov_b32_e32 v38, 0
	v_mov_b32_e32 v43, 0
	s_and_saveexec_b64 s[0:1], s[38:39]
	s_cbranch_execz .LBB0_1331
	v_lshl_add_u64 v[44:45], v[66:67], 2, v[162:163]
	v_mov_b32_e32 v43, v209
.LBB0_1331:
	s_or_b64 exec, exec, s[0:1]
	s_waitcnt lgkmcnt(0)
	v_mul_f32_e32 v39, v39, v43
	v_cvt_pk_bf16_f32 v39, v39, s0
	ds_write_b16 v47, v39 offset:64
	s_and_saveexec_b64 s[0:1], s[40:41]
	s_cbranch_execz .LBB0_1333
	v_lshl_add_u64 v[38:39], v[66:67], 2, v[162:163]
	v_mov_b32_e32 v38, v210
.LBB0_1333:
	s_or_b64 exec, exec, s[0:1]
	s_waitcnt lgkmcnt(0)
	v_mul_f32_e32 v38, v40, v38
	v_cvt_pk_bf16_f32 v38, v38, s0
	ds_write_b16 v48, v38 offset:64
	v_mov_b32_e32 v38, 0
	v_mov_b32_e32 v39, 0
	s_and_saveexec_b64 s[0:1], s[42:43]
	s_cbranch_execz .LBB0_1335
	v_lshl_add_u64 v[44:45], v[66:67], 2, v[162:163]
	v_mov_b32_e32 v39, v211
.LBB0_1335:
	s_or_b64 exec, exec, s[0:1]
	s_waitcnt lgkmcnt(0)
	v_mul_f32_e32 v39, v41, v39
	v_cvt_pk_bf16_f32 v39, v39, s0
	ds_write_b16 v42, v39 offset:64
	s_and_saveexec_b64 s[0:1], vcc
	s_cbranch_execz .LBB0_1337
	v_lshl_add_u64 v[38:39], v[66:67], 2, v[162:163]
	v_mov_b32_e32 v38, v208
.LBB0_1337:
	s_or_b64 exec, exec, s[0:1]
	s_waitcnt lgkmcnt(0)
	v_mul_f32_e32 v34, v34, v38
	v_cvt_pk_bf16_f32 v34, v34, s0
	ds_write_b16 v46, v34 offset:96
	v_mov_b32_e32 v34, 0
	v_mov_b32_e32 v38, 0
	s_and_saveexec_b64 s[0:1], s[38:39]
	s_cbranch_execz .LBB0_1339
	v_lshl_add_u64 v[38:39], v[66:67], 2, v[162:163]
	v_mov_b32_e32 v38, v209
.LBB0_1339:
	s_or_b64 exec, exec, s[0:1]
	s_waitcnt lgkmcnt(0)
	v_mul_f32_e32 v35, v35, v38
	v_cvt_pk_bf16_f32 v35, v35, s0
	ds_write_b16 v47, v35 offset:96
	s_and_saveexec_b64 s[0:1], s[40:41]
	s_cbranch_execz .LBB0_1341
	v_lshl_add_u64 v[34:35], v[66:67], 2, v[162:163]
	v_mov_b32_e32 v34, v210
.LBB0_1341:
	s_or_b64 exec, exec, s[0:1]
	s_waitcnt lgkmcnt(0)
	v_mul_f32_e32 v34, v36, v34
	v_cvt_pk_bf16_f32 v34, v34, s0
	ds_write_b16 v48, v34 offset:96
	v_mov_b32_e32 v34, 0
	v_mov_b32_e32 v35, 0
	s_and_saveexec_b64 s[0:1], s[42:43]
	s_cbranch_execz .LBB0_1343
	v_lshl_add_u64 v[38:39], v[66:67], 2, v[162:163]
	v_mov_b32_e32 v35, v211
.LBB0_1343:
	s_or_b64 exec, exec, s[0:1]
	s_waitcnt lgkmcnt(0)
	v_mul_f32_e32 v35, v37, v35
	v_cvt_pk_bf16_f32 v35, v35, s0
	ds_write_b16 v42, v35 offset:96
	v_or_b32_e32 v35, 32, v66
	v_cmp_gt_i32_e32 vcc, s60, v35
	s_and_saveexec_b64 s[0:1], vcc
	s_cbranch_execz .LBB0_1345
	v_lshl_add_u64 v[36:37], v[66:67], 2, v[162:163]
	v_mov_b32_e32 v34, v216
.LBB0_1345:
	s_or_b64 exec, exec, s[0:1]
	s_waitcnt lgkmcnt(0)
	v_mul_f32_e32 v30, v30, v34
	v_mul_lo_u32 v35, v35, s23
	v_cvt_pk_bf16_f32 v34, v30, s0
	v_lshl_add_u32 v30, v68, 1, v35
	ds_write_b16 v30, v34
	v_or_b32_e32 v34, 33, v66
	v_cmp_gt_i32_e64 s[38:39], s60, v34
	v_mov_b32_e32 v34, 0
	v_mov_b32_e32 v36, 0
	s_and_saveexec_b64 s[0:1], s[38:39]
	s_cbranch_execz .LBB0_1347
	v_lshl_add_u64 v[36:37], v[66:67], 2, v[162:163]
	v_mov_b32_e32 v36, v217
.LBB0_1347:
	s_or_b64 exec, exec, s[0:1]
	s_waitcnt lgkmcnt(0)
	v_mul_f32_e32 v31, v31, v36
	v_add_u32_e32 v35, 0x110, v35
	v_cvt_pk_bf16_f32 v36, v31, s0
	v_lshl_add_u32 v31, v68, 1, v35
	ds_write_b16 v31, v36
	v_or_b32_e32 v36, 34, v66
	v_cmp_gt_i32_e64 s[40:41], s60, v36
	s_and_saveexec_b64 s[0:1], s[40:41]
	s_cbranch_execz .LBB0_1349
	v_lshl_add_u64 v[36:37], v[66:67], 2, v[162:163]
	v_mov_b32_e32 v34, v218
.LBB0_1349:
	s_or_b64 exec, exec, s[0:1]
	s_waitcnt lgkmcnt(0)
	v_mul_f32_e32 v32, v32, v34
	v_cvt_pk_bf16_f32 v34, v32, s0
	v_add_u32_e32 v32, 0x110, v35
	v_lshl_add_u32 v32, v68, 1, v32
	ds_write_b16 v32, v34
	v_or_b32_e32 v34, 35, v66
	v_cmp_gt_i32_e64 s[42:43], s60, v34
	v_mov_b32_e32 v34, 0
	v_mov_b32_e32 v35, 0
	s_and_saveexec_b64 s[0:1], s[42:43]
	s_cbranch_execz .LBB0_1351
	v_lshl_add_u64 v[36:37], v[66:67], 2, v[162:163]
	v_mov_b32_e32 v35, v219
.LBB0_1351:
	s_or_b64 exec, exec, s[0:1]
	s_waitcnt lgkmcnt(0)
	v_mul_f32_e32 v33, v33, v35
	v_cvt_pk_bf16_f32 v33, v33, s0
	ds_write_b16 v32, v33 offset:272
	s_and_saveexec_b64 s[0:1], vcc
	s_cbranch_execz .LBB0_1353
	v_lshl_add_u64 v[34:35], v[66:67], 2, v[162:163]
	v_mov_b32_e32 v34, v216
; __device__ __forceinline__ u16 f2bf(float f) { return (u16)(pack2(f, 0.f) & 0xffffu); }
; template <int NT, class VF, class RP>
; __device__ __forceinline__ void epi_staged_bf16(f32x4 (&acc)[4][NT], int r0, int c0, unsigned char* smem, VF vf, RP rowptr) {
;     ...
;   __syncthreads();
; #pragma unroll
;   for (int mi = 0; mi < 4; ++mi)
; #pragma unroll
;     for (int ni = 0; ni < NT; ++ni)
; #pragma unroll
;       for (int j = 0; j < 4; ++j) {
;         const int r = r0 + mi * 16 + j, c = c0 + ni * 16;
;         Ts[r * PITCH + c] = f2bf(vf(r, c, acc[mi][ni][j]));
;       }
; __device__ __forceinline__ void phase_moe_down(const Params& p, int l, bool last, unsigned char* smem) {
;     ...
;     auto epi = [&](f32x4(&acc)[4][4], int r0, int c0) {
;       auto vf = [&](int r, int, float v) { return (r < mvalid ? gate[r] : 0.f) * v; };
;       auto rp = [&](int r) -> u16* { return r < mvalid ? yb + (size_t)r * 1024 : nullptr; };
;       epi_staged_bf16<4>(acc, r0, c0, smem, vf, rp);
.LBB0_1353:
	s_or_b64 exec, exec, s[0:1]
	s_waitcnt lgkmcnt(0)
	v_mul_f32_e32 v26, v26, v34
	v_cvt_pk_bf16_f32 v26, v26, s0
	ds_write_b16 v30, v26 offset:32
	v_mov_b32_e32 v26, 0
	v_mov_b32_e32 v33, 0
	s_and_saveexec_b64 s[0:1], s[38:39]
	s_cbranch_execz .LBB0_1355
	v_lshl_add_u64 v[34:35], v[66:67], 2, v[162:163]
	v_mov_b32_e32 v33, v217
.LBB0_1355:
	s_or_b64 exec, exec, s[0:1]
	s_waitcnt lgkmcnt(0)
	v_mul_f32_e32 v27, v27, v33
	v_cvt_pk_bf16_f32 v27, v27, s0
	ds_write_b16 v31, v27 offset:32
	s_and_saveexec_b64 s[0:1], s[40:41]
	s_cbranch_execz .LBB0_1357
	v_lshl_add_u64 v[26:27], v[66:67], 2, v[162:163]
	v_mov_b32_e32 v26, v218
.LBB0_1357:
	s_or_b64 exec, exec, s[0:1]
	s_waitcnt lgkmcnt(0)
	v_mul_f32_e32 v26, v28, v26
	v_cvt_pk_bf16_f32 v26, v26, s0
	v_mov_b32_e32 v27, 0
	v_mov_b32_e32 v28, 0
	ds_write_b16 v32, v26 offset:32
	s_and_saveexec_b64 s[0:1], s[42:43]
	s_cbranch_execz .LBB0_1359
	v_lshl_add_u64 v[34:35], v[66:67], 2, v[162:163]
	v_mov_b32_e32 v28, v219
.LBB0_1359:
	s_or_b64 exec, exec, s[0:1]
	s_waitcnt lgkmcnt(0)
	v_mul_f32_e32 v28, v29, v28
	v_add_u32_e32 v26, 0x110, v32
	v_cvt_pk_bf16_f32 v28, v28, s0
	ds_write_b16 v26, v28 offset:32
	s_and_saveexec_b64 s[0:1], vcc
	s_cbranch_execz .LBB0_1361
	v_lshl_add_u64 v[28:29], v[66:67], 2, v[162:163]
	v_mov_b32_e32 v27, v216
.LBB0_1361:
	s_or_b64 exec, exec, s[0:1]
	s_waitcnt lgkmcnt(0)
	v_mul_f32_e32 v22, v22, v27
	v_cvt_pk_bf16_f32 v22, v22, s0
	ds_write_b16 v30, v22 offset:64
	v_mov_b32_e32 v22, 0
	v_mov_b32_e32 v27, 0
	s_and_saveexec_b64 s[0:1], s[38:39]
	s_cbranch_execz .LBB0_1363
	v_lshl_add_u64 v[28:29], v[66:67], 2, v[162:163]
	v_mov_b32_e32 v27, v217
.LBB0_1363:
	s_or_b64 exec, exec, s[0:1]
	s_waitcnt lgkmcnt(0)
	v_mul_f32_e32 v23, v23, v27
	v_cvt_pk_bf16_f32 v23, v23, s0
	ds_write_b16 v31, v23 offset:64
	s_and_saveexec_b64 s[0:1], s[40:41]
	s_cbranch_execz .LBB0_1365
	v_lshl_add_u64 v[22:23], v[66:67], 2, v[162:163]
	v_mov_b32_e32 v22, v218
.LBB0_1365:
	s_or_b64 exec, exec, s[0:1]
	s_waitcnt lgkmcnt(0)
	v_mul_f32_e32 v22, v24, v22
	v_cvt_pk_bf16_f32 v22, v22, s0
	ds_write_b16 v32, v22 offset:64
	v_mov_b32_e32 v22, 0
	v_mov_b32_e32 v23, 0
	s_and_saveexec_b64 s[0:1], s[42:43]
	s_cbranch_execz .LBB0_1367
	v_lshl_add_u64 v[28:29], v[66:67], 2, v[162:163]
	v_mov_b32_e32 v23, v219
.LBB0_1367:
	s_or_b64 exec, exec, s[0:1]
	s_waitcnt lgkmcnt(0)
	v_mul_f32_e32 v23, v25, v23
	v_cvt_pk_bf16_f32 v23, v23, s0
	ds_write_b16 v26, v23 offset:64
	s_and_saveexec_b64 s[0:1], vcc
	s_cbranch_execz .LBB0_1369
	v_lshl_add_u64 v[22:23], v[66:67], 2, v[162:163]
	v_mov_b32_e32 v22, v216
.LBB0_1369:
	s_or_b64 exec, exec, s[0:1]
	s_waitcnt lgkmcnt(0)
	v_mul_f32_e32 v18, v18, v22
	v_cvt_pk_bf16_f32 v18, v18, s0
	ds_write_b16 v30, v18 offset:96
	v_mov_b32_e32 v18, 0
	v_mov_b32_e32 v22, 0
	s_and_saveexec_b64 s[0:1], s[38:39]
	s_cbranch_execz .LBB0_1371
	v_lshl_add_u64 v[22:23], v[66:67], 2, v[162:163]
	v_mov_b32_e32 v22, v217
.LBB0_1371:
	s_or_b64 exec, exec, s[0:1]
	s_waitcnt lgkmcnt(0)
	v_mul_f32_e32 v19, v19, v22
	v_cvt_pk_bf16_f32 v19, v19, s0
	ds_write_b16 v31, v19 offset:96
	s_and_saveexec_b64 s[0:1], s[40:41]
	s_cbranch_execz .LBB0_1373
	v_lshl_add_u64 v[18:19], v[66:67], 2, v[162:163]
	v_mov_b32_e32 v18, v218
.LBB0_1373:
	s_or_b64 exec, exec, s[0:1]
	s_waitcnt lgkmcnt(0)
	v_mul_f32_e32 v18, v20, v18
	v_cvt_pk_bf16_f32 v18, v18, s0
	ds_write_b16 v32, v18 offset:96
	v_mov_b32_e32 v18, 0
	v_mov_b32_e32 v19, 0
	s_and_saveexec_b64 s[0:1], s[42:43]
	s_cbranch_execz .LBB0_1375
	v_lshl_add_u64 v[22:23], v[66:67], 2, v[162:163]
	v_mov_b32_e32 v19, v219
.LBB0_1375:
	s_or_b64 exec, exec, s[0:1]
	s_waitcnt lgkmcnt(0)
	v_mul_f32_e32 v19, v21, v19
	v_cvt_pk_bf16_f32 v19, v19, s0
	ds_write_b16 v26, v19 offset:96
	v_or_b32_e32 v19, 48, v66
	v_cmp_gt_i32_e32 vcc, s60, v19
	s_and_saveexec_b64 s[0:1], vcc
	s_cbranch_execz .LBB0_1377
	v_lshl_add_u64 v[20:21], v[66:67], 2, v[162:163]
	v_mov_b32_e32 v18, v220
.LBB0_1377:
	s_or_b64 exec, exec, s[0:1]
	s_waitcnt lgkmcnt(0)
	v_mul_f32_e32 v14, v14, v18
	v_mul_lo_u32 v19, v19, s23
	v_cvt_pk_bf16_f32 v18, v14, s0
	v_lshl_add_u32 v14, v68, 1, v19
	ds_write_b16 v14, v18
	v_or_b32_e32 v18, 49, v66
	v_cmp_gt_i32_e64 s[38:39], s60, v18
	v_mov_b32_e32 v18, 0
	v_mov_b32_e32 v20, 0
	s_and_saveexec_b64 s[0:1], s[38:39]
	s_cbranch_execz .LBB0_1379
	v_lshl_add_u64 v[20:21], v[66:67], 2, v[162:163]
	v_mov_b32_e32 v20, v221
.LBB0_1379:
	s_or_b64 exec, exec, s[0:1]
	s_waitcnt lgkmcnt(0)
	v_mul_f32_e32 v15, v15, v20
	v_add_u32_e32 v19, 0x110, v19
	v_cvt_pk_bf16_f32 v20, v15, s0
	v_lshl_add_u32 v15, v68, 1, v19
	ds_write_b16 v15, v20
	v_or_b32_e32 v20, 50, v66
	v_cmp_gt_i32_e64 s[40:41], s60, v20
	s_and_saveexec_b64 s[0:1], s[40:41]
	s_cbranch_execz .LBB0_1381
	v_lshl_add_u64 v[20:21], v[66:67], 2, v[162:163]
	v_mov_b32_e32 v18, v222
; __device__ __forceinline__ u16 f2bf(float f) { return (u16)(pack2(f, 0.f) & 0xffffu); }
; template <int NT, class VF, class RP>
; __device__ __forceinline__ void epi_staged_bf16(f32x4 (&acc)[4][NT], int r0, int c0, unsigned char* smem, VF vf, RP rowptr) {
;     ...
;   __syncthreads();
; #pragma unroll
;   for (int mi = 0; mi < 4; ++mi)
; #pragma unroll
;     for (int ni = 0; ni < NT; ++ni)
; #pragma unroll
;       for (int j = 0; j < 4; ++j) {
;         const int r = r0 + mi * 16 + j, c = c0 + ni * 16;
;         Ts[r * PITCH + c] = f2bf(vf(r, c, acc[mi][ni][j]));
;       }
;   __syncthreads();
; #pragma unroll
;   for (int i = 0; i < CPR / 2; ++i) {
;     const int c = t + 256 * i, row = c / CPR, ch = c % CPR;
;     u16* d = rowptr(row);
;     if (d) *(u32x4*)(d + ch * 8) = *(const u32x4*)(Ts + row * PITCH + ch * 8);
;   }
; __device__ __forceinline__ void phase_moe_down(const Params& p, int l, bool last, unsigned char* smem) {
;     ...
;     auto epi = [&](f32x4(&acc)[4][4], int r0, int c0) {
;       auto vf = [&](int r, int, float v) { return (r < mvalid ? gate[r] : 0.f) * v; };
;       auto rp = [&](int r) -> u16* { return r < mvalid ? yb + (size_t)r * 1024 : nullptr; };
;       epi_staged_bf16<4>(acc, r0, c0, smem, vf, rp);
.LBB0_1381:
	s_or_b64 exec, exec, s[0:1]
	s_waitcnt lgkmcnt(0)
	v_mul_f32_e32 v16, v16, v18
	v_cvt_pk_bf16_f32 v18, v16, s0
	v_add_u32_e32 v16, 0x110, v19
	v_lshl_add_u32 v16, v68, 1, v16
	ds_write_b16 v16, v18
	v_or_b32_e32 v18, 51, v66
	v_cmp_gt_i32_e64 s[42:43], s60, v18
	v_mov_b32_e32 v18, 0
	v_mov_b32_e32 v19, 0
	s_and_saveexec_b64 s[0:1], s[42:43]
	s_cbranch_execz .LBB0_1383
	v_lshl_add_u64 v[20:21], v[66:67], 2, v[162:163]
	v_mov_b32_e32 v19, v223
.LBB0_1383:
	s_or_b64 exec, exec, s[0:1]
	s_waitcnt lgkmcnt(0)
	v_mul_f32_e32 v17, v17, v19
	v_cvt_pk_bf16_f32 v17, v17, s0
	ds_write_b16 v16, v17 offset:272
	s_and_saveexec_b64 s[0:1], vcc
	s_cbranch_execz .LBB0_1385
	v_lshl_add_u64 v[18:19], v[66:67], 2, v[162:163]
	v_mov_b32_e32 v18, v220
.LBB0_1385:
	s_or_b64 exec, exec, s[0:1]
	s_waitcnt lgkmcnt(0)
	v_mul_f32_e32 v10, v10, v18
	v_cvt_pk_bf16_f32 v10, v10, s0
	ds_write_b16 v14, v10 offset:32
	v_mov_b32_e32 v10, 0
	v_mov_b32_e32 v17, 0
	s_and_saveexec_b64 s[0:1], s[38:39]
	s_cbranch_execz .LBB0_1387
	v_lshl_add_u64 v[18:19], v[66:67], 2, v[162:163]
	v_mov_b32_e32 v17, v221
.LBB0_1387:
	s_or_b64 exec, exec, s[0:1]
	s_waitcnt lgkmcnt(0)
	v_mul_f32_e32 v11, v11, v17
	v_cvt_pk_bf16_f32 v11, v11, s0
	ds_write_b16 v15, v11 offset:32
	s_and_saveexec_b64 s[0:1], s[40:41]
	s_cbranch_execz .LBB0_1389
	v_lshl_add_u64 v[10:11], v[66:67], 2, v[162:163]
	v_mov_b32_e32 v10, v222
.LBB0_1389:
	s_or_b64 exec, exec, s[0:1]
	s_waitcnt lgkmcnt(0)
	v_mul_f32_e32 v10, v12, v10
	v_cvt_pk_bf16_f32 v10, v10, s0
	v_mov_b32_e32 v11, 0
	v_mov_b32_e32 v12, 0
	ds_write_b16 v16, v10 offset:32
	s_and_saveexec_b64 s[0:1], s[42:43]
	s_cbranch_execz .LBB0_1391
	v_lshl_add_u64 v[18:19], v[66:67], 2, v[162:163]
	v_mov_b32_e32 v12, v223
.LBB0_1391:
	s_or_b64 exec, exec, s[0:1]
	s_waitcnt lgkmcnt(0)
	v_mul_f32_e32 v12, v13, v12
	v_add_u32_e32 v10, 0x110, v16
	v_cvt_pk_bf16_f32 v12, v12, s0
	ds_write_b16 v10, v12 offset:32
	s_and_saveexec_b64 s[0:1], vcc
	s_cbranch_execz .LBB0_1393
	v_lshl_add_u64 v[12:13], v[66:67], 2, v[162:163]
	v_mov_b32_e32 v11, v220
.LBB0_1393:
	s_or_b64 exec, exec, s[0:1]
	s_waitcnt lgkmcnt(0)
	v_mul_f32_e32 v6, v6, v11
	v_cvt_pk_bf16_f32 v6, v6, s0
	ds_write_b16 v14, v6 offset:64
	v_mov_b32_e32 v6, 0
	v_mov_b32_e32 v11, 0
	s_and_saveexec_b64 s[0:1], s[38:39]
	s_cbranch_execz .LBB0_1395
	v_lshl_add_u64 v[12:13], v[66:67], 2, v[162:163]
	v_mov_b32_e32 v11, v221
.LBB0_1395:
	s_or_b64 exec, exec, s[0:1]
	s_waitcnt lgkmcnt(0)
	v_mul_f32_e32 v7, v7, v11
	v_cvt_pk_bf16_f32 v7, v7, s0
	ds_write_b16 v15, v7 offset:64
	s_and_saveexec_b64 s[0:1], s[40:41]
	s_cbranch_execz .LBB0_1397
	v_lshl_add_u64 v[6:7], v[66:67], 2, v[162:163]
	v_mov_b32_e32 v6, v222
.LBB0_1397:
	s_or_b64 exec, exec, s[0:1]
	s_waitcnt lgkmcnt(0)
	v_mul_f32_e32 v6, v8, v6
	v_cvt_pk_bf16_f32 v6, v6, s0
	ds_write_b16 v16, v6 offset:64
	v_mov_b32_e32 v6, 0
	v_mov_b32_e32 v7, 0
	s_and_saveexec_b64 s[0:1], s[42:43]
	s_cbranch_execz .LBB0_1399
	v_lshl_add_u64 v[12:13], v[66:67], 2, v[162:163]
	v_mov_b32_e32 v7, v223
.LBB0_1399:
	s_or_b64 exec, exec, s[0:1]
	s_waitcnt lgkmcnt(0)
	v_mul_f32_e32 v7, v9, v7
	v_cvt_pk_bf16_f32 v7, v7, s0
	ds_write_b16 v10, v7 offset:64
	s_and_saveexec_b64 s[0:1], vcc
	s_cbranch_execz .LBB0_1401
	v_lshl_add_u64 v[6:7], v[66:67], 2, v[162:163]
	v_mov_b32_e32 v6, v220
.LBB0_1401:
	s_or_b64 exec, exec, s[0:1]
	s_waitcnt lgkmcnt(0)
	v_mul_f32_e32 v2, v2, v6
	v_cvt_pk_bf16_f32 v2, v2, s0
	ds_write_b16 v14, v2 offset:96
	v_mov_b32_e32 v2, 0
	v_mov_b32_e32 v6, 0
	s_and_saveexec_b64 s[0:1], s[38:39]
	s_cbranch_execz .LBB0_1403
	v_lshl_add_u64 v[6:7], v[66:67], 2, v[162:163]
	v_mov_b32_e32 v6, v221
.LBB0_1403:
	s_or_b64 exec, exec, s[0:1]
	s_waitcnt lgkmcnt(0)
	v_mul_f32_e32 v3, v3, v6
	v_cvt_pk_bf16_f32 v3, v3, s0
	ds_write_b16 v15, v3 offset:96
	s_and_saveexec_b64 s[0:1], s[40:41]
	s_cbranch_execz .LBB0_1405
	v_lshl_add_u64 v[2:3], v[66:67], 2, v[162:163]
	v_mov_b32_e32 v2, v222
.LBB0_1405:
	s_or_b64 exec, exec, s[0:1]
	s_waitcnt lgkmcnt(0)
	v_mul_f32_e32 v2, v4, v2
	v_cvt_pk_bf16_f32 v2, v2, s0
	ds_write_b16 v16, v2 offset:96
	v_mov_b32_e32 v2, 0
	s_and_saveexec_b64 s[0:1], s[42:43]
	s_cbranch_execz .LBB0_1407
	v_lshl_add_u64 v[2:3], v[66:67], 2, v[162:163]
	v_mov_b32_e32 v2, v223
.LBB0_1407:
	s_or_b64 exec, exec, s[0:1]
	s_waitcnt lgkmcnt(0)
	v_mul_f32_e32 v2, v5, v2
	v_cvt_pk_bf16_f32 v2, v2, s0
	ds_write_b16 v10, v2 offset:96
	v_ashrrev_i32_e32 v2, 31, v0
	v_lshrrev_b32_e32 v2, 28, v2
	v_add_u32_e32 v2, v0, v2
	v_ashrrev_i32_e32 v2, 4, v2
	v_cmp_gt_i32_e64 s[38:39], s60, v2
	v_cmp_ne_u64_e64 s[40:41], 0, v[164:165]
	v_cmp_eq_u64_e32 vcc, 0, v[164:165]
	s_and_b64 s[8:9], s[38:39], s[40:41]
	s_waitcnt lgkmcnt(0)
	s_barrier
	s_and_saveexec_b64 s[0:1], s[8:9]
	s_cbranch_execz .LBB0_1409
	v_ashrrev_i32_e32 v3, 31, v2
	v_lshlrev_b64 v[6:7], 11, v[2:3]
	v_lshlrev_b32_e32 v3, 4, v2
	v_sub_u32_e32 v8, v0, v3
	v_mul_lo_u32 v2, v2, s23
	v_lshl_add_u32 v2, v8, 4, v2
	ds_read_b128 v[2:5], v2
	v_lshlrev_b32_e32 v8, 3, v8
	v_lshl_add_u64 v[6:7], v[160:161], 0, v[6:7]
	v_ashrrev_i32_e32 v9, 31, v8
	v_lshl_add_u64 v[6:7], v[8:9], 1, v[6:7]
	s_waitcnt lgkmcnt(0)
	global_store_dwordx4 v[6:7], v[2:5], off

; __device__ __forceinline__ u16 f2bf(float f) { return (u16)(pack2(f, 0.f) & 0xffffu); }
; template <int NT, class VF, class RP>
; __device__ __forceinline__ void epi_staged_bf16(f32x4 (&acc)[4][NT], int r0, int c0, unsigned char* smem, VF vf, RP rowptr) {
;     ...
;   __syncthreads();
; #pragma unroll
;   for (int mi = 0; mi < 4; ++mi)
; #pragma unroll
;     for (int ni = 0; ni < NT; ++ni)
; #pragma unroll
;       for (int j = 0; j < 4; ++j) {
;         const int r = r0 + mi * 16 + j, c = c0 + ni * 16;
;         Ts[r * PITCH + c] = f2bf(vf(r, c, acc[mi][ni][j]));
;       }
; __device__ __forceinline__ void phase_moe_down(const Params& p, int l, bool last, unsigned char* smem) {
;     ...
;     auto epi = [&](f32x4(&acc)[4][4], int r0, int c0) {
;       auto vf = [&](int r, int, float v) { return (r < mvalid ? gate[r] : 0.f) * v; };
;       auto rp = [&](int r) -> u16* { return r < mvalid ? yb + (size_t)r * 1024 : nullptr; };
;       epi_staged_bf16<4>(acc, r0, c0, smem, vf, rp);
.LBB0_1516:
	v_lshl_or_b32 v2, v0, 2, v190
	v_mov_b32_e32 v0, v187
	v_cmp_gt_i32_e32 vcc, s60, v2
	s_waitcnt lgkmcnt(4)
	v_mov_b32_e32 v70, 0
	v_ashrrev_i32_e32 v3, 31, v2
	v_mov_b32_e32 v69, 0
	s_waitcnt lgkmcnt(0)
	s_barrier
	v_lshl_add_u64 v[230:231], v[2:3], 2, v[162:163]
	global_load_dwordx4 v[204:207], v[230:231], off offset:0
	global_load_dwordx4 v[208:211], v[230:231], off offset:64
	global_load_dwordx4 v[216:219], v[230:231], off offset:128
	global_load_dwordx4 v[220:223], v[230:231], off offset:192
	s_waitcnt vmcnt(0)
	s_and_saveexec_b64 s[0:1], vcc
	s_xor_b64 s[0:1], exec, s[0:1]
	s_cbranch_execz .LBB0_1518
	v_lshl_add_u64 v[68:69], v[2:3], 2, v[162:163]
	v_mov_b32_e32 v69, v204
.LBB0_1518:
	s_or_b64 exec, exec, s[0:1]
	v_lshl_or_b32 v68, v188, 6, v189
	s_waitcnt lgkmcnt(0)
	v_mul_f32_e32 v64, v64, v69
	v_mul_lo_u32 v69, v2, s22
	v_lshlrev_b32_e32 v71, 1, v68
	v_cvt_pk_bf16_f32 v64, v64, s0
	v_lshl_add_u32 v71, v69, 1, v71
	ds_write_b16 v71, v64
	v_or_b32_e32 v64, 1, v2
	v_cmp_gt_i32_e64 s[38:39], s60, v64
	s_and_saveexec_b64 s[0:1], s[38:39]
	s_cbranch_execz .LBB0_1520
	v_lshl_add_u64 v[70:71], v[2:3], 2, v[162:163]
	v_mov_b32_e32 v70, v205
.LBB0_1520:
	s_or_b64 exec, exec, s[0:1]
	s_waitcnt lgkmcnt(0)
	v_mul_f32_e32 v65, v65, v70
	v_cvt_pk_bf16_f32 v70, v65, s0
	v_mul_lo_u32 v65, v64, s23
	v_lshl_add_u32 v64, v68, 1, v65
	ds_write_b16 v64, v70
	v_or_b32_e32 v70, 2, v2
	v_cmp_gt_i32_e64 s[40:41], s60, v70
	v_mov_b32_e32 v70, 0
	v_mov_b32_e32 v71, 0
	s_and_saveexec_b64 s[0:1], s[40:41]
	s_cbranch_execz .LBB0_1522
	v_lshl_add_u64 v[72:73], v[2:3], 2, v[162:163]
	v_mov_b32_e32 v71, v206
.LBB0_1522:
	s_or_b64 exec, exec, s[0:1]
	s_waitcnt lgkmcnt(0)
	v_mul_f32_e32 v66, v66, v71
	v_add_u32_e32 v65, 0x110, v65
	v_cvt_pk_bf16_f32 v66, v66, s0
	v_lshl_add_u32 v65, v68, 1, v65
	ds_write_b16 v65, v66
	v_or_b32_e32 v66, 3, v2
	v_cmp_gt_i32_e64 s[42:43], s60, v66
	s_and_saveexec_b64 s[0:1], s[42:43]
	s_cbranch_execz .LBB0_1524
	v_lshl_add_u64 v[70:71], v[2:3], 2, v[162:163]
	v_mov_b32_e32 v70, v207
.LBB0_1524:
	s_or_b64 exec, exec, s[0:1]
	s_waitcnt lgkmcnt(0)
	v_mul_f32_e32 v66, v67, v70
	v_cvt_pk_bf16_f32 v66, v66, s0
	ds_write_b16 v65, v66 offset:272
	v_mov_b32_e32 v67, 0
	v_mov_b32_e32 v66, 0
	s_and_saveexec_b64 s[0:1], vcc
	s_cbranch_execz .LBB0_1526
	v_lshl_add_u64 v[70:71], v[2:3], 2, v[162:163]
	v_mov_b32_e32 v66, v204
.LBB0_1526:
	s_or_b64 exec, exec, s[0:1]
	s_waitcnt lgkmcnt(0)
	v_mul_f32_e32 v60, v60, v66
	v_lshlrev_b32_e32 v66, 1, v69
	v_cvt_pk_bf16_f32 v60, v60, s0
	v_lshl_add_u32 v66, v68, 1, v66
	ds_write_b16 v66, v60 offset:32
	s_and_saveexec_b64 s[0:1], s[38:39]
	s_cbranch_execz .LBB0_1528
	v_lshl_add_u64 v[70:71], v[2:3], 2, v[162:163]
	v_mov_b32_e32 v67, v205
.LBB0_1528:
	s_or_b64 exec, exec, s[0:1]
	s_waitcnt lgkmcnt(0)
	v_mul_f32_e32 v60, v61, v67
	v_cvt_pk_bf16_f32 v60, v60, s0
	ds_write_b16 v64, v60 offset:32
	v_mov_b32_e32 v61, 0
	v_mov_b32_e32 v60, 0
	s_and_saveexec_b64 s[0:1], s[40:41]
	s_cbranch_execz .LBB0_1530
	v_lshl_add_u64 v[70:71], v[2:3], 2, v[162:163]
	v_mov_b32_e32 v60, v206
.LBB0_1530:
	s_or_b64 exec, exec, s[0:1]
	s_waitcnt lgkmcnt(0)
	v_mul_f32_e32 v60, v62, v60
	v_cvt_pk_bf16_f32 v60, v60, s0
	ds_write_b16 v65, v60 offset:32
	s_and_saveexec_b64 s[0:1], s[42:43]
	s_cbranch_execz .LBB0_1532
	v_lshl_add_u64 v[60:61], v[2:3], 2, v[162:163]
	v_mov_b32_e32 v61, v207
.LBB0_1532:
	s_or_b64 exec, exec, s[0:1]
	s_waitcnt lgkmcnt(0)
	v_mul_f32_e32 v61, v63, v61
	v_add_u32_e32 v60, 0x110, v65
	v_cvt_pk_bf16_f32 v61, v61, s0
	ds_write_b16 v60, v61 offset:32
	v_mov_b32_e32 v61, 0
	v_mov_b32_e32 v62, 0
	s_and_saveexec_b64 s[0:1], vcc
	s_cbranch_execz .LBB0_1534
	v_lshl_add_u64 v[62:63], v[2:3], 2, v[162:163]
	v_mov_b32_e32 v62, v204
.LBB0_1534:
	s_or_b64 exec, exec, s[0:1]
	s_waitcnt lgkmcnt(0)
	v_mul_f32_e32 v56, v56, v62
	v_cvt_pk_bf16_f32 v56, v56, s0
	ds_write_b16 v66, v56 offset:64
	s_and_saveexec_b64 s[0:1], s[38:39]
	s_cbranch_execz .LBB0_1536
	v_lshl_add_u64 v[62:63], v[2:3], 2, v[162:163]
	v_mov_b32_e32 v61, v205
.LBB0_1536:
	s_or_b64 exec, exec, s[0:1]
	s_waitcnt lgkmcnt(0)
	v_mul_f32_e32 v56, v57, v61
	v_cvt_pk_bf16_f32 v56, v56, s0
	ds_write_b16 v64, v56 offset:64
	v_mov_b32_e32 v56, 0
	v_mov_b32_e32 v57, 0
	s_and_saveexec_b64 s[0:1], s[40:41]
	s_cbranch_execz .LBB0_1538
	v_lshl_add_u64 v[62:63], v[2:3], 2, v[162:163]
	v_mov_b32_e32 v57, v206
.LBB0_1538:
	s_or_b64 exec, exec, s[0:1]
	s_waitcnt lgkmcnt(0)
	v_mul_f32_e32 v57, v58, v57
	v_cvt_pk_bf16_f32 v57, v57, s0
	ds_write_b16 v65, v57 offset:64
	s_and_saveexec_b64 s[0:1], s[42:43]
	s_cbranch_execz .LBB0_1540
	v_lshl_add_u64 v[56:57], v[2:3], 2, v[162:163]
	v_mov_b32_e32 v56, v207
.LBB0_1540:
	s_or_b64 exec, exec, s[0:1]
	s_waitcnt lgkmcnt(0)
	v_mul_f32_e32 v56, v59, v56
	v_cvt_pk_bf16_f32 v56, v56, s0
	ds_write_b16 v60, v56 offset:64
	v_mov_b32_e32 v56, 0
	v_mov_b32_e32 v57, 0
	s_and_saveexec_b64 s[0:1], vcc
	s_cbranch_execz .LBB0_1542
	v_lshl_add_u64 v[58:59], v[2:3], 2, v[162:163]
	v_mov_b32_e32 v57, v204
.LBB0_1542:
	s_or_b64 exec, exec, s[0:1]
	s_waitcnt lgkmcnt(0)
	v_mul_f32_e32 v52, v52, v57
	v_cvt_pk_bf16_f32 v52, v52, s0
	ds_write_b16 v66, v52 offset:96
	s_and_saveexec_b64 s[0:1], s[38:39]
	s_cbranch_execz .LBB0_1544
	v_lshl_add_u64 v[56:57], v[2:3], 2, v[162:163]
	v_mov_b32_e32 v56, v205
.LBB0_1544:
	s_or_b64 exec, exec, s[0:1]
	s_waitcnt lgkmcnt(0)
	v_mul_f32_e32 v52, v53, v56
	v_cvt_pk_bf16_f32 v52, v52, s0
	ds_write_b16 v64, v52 offset:96
	v_mov_b32_e32 v52, 0
	v_mov_b32_e32 v53, 0
	s_and_saveexec_b64 s[0:1], s[40:41]
	s_cbranch_execz .LBB0_1546
	v_lshl_add_u64 v[56:57], v[2:3], 2, v[162:163]
	v_mov_b32_e32 v53, v206
; __device__ __forceinline__ u16 f2bf(float f) { return (u16)(pack2(f, 0.f) & 0xffffu); }
; template <int NT, class VF, class RP>
; __device__ __forceinline__ void epi_staged_bf16(f32x4 (&acc)[4][NT], int r0, int c0, unsigned char* smem, VF vf, RP rowptr) {
;     ...
; #pragma unroll
;   for (int mi = 0; mi < 4; ++mi)
; #pragma unroll
;     for (int ni = 0; ni < NT; ++ni)
; #pragma unroll
;       for (int j = 0; j < 4; ++j) {
;         const int r = r0 + mi * 16 + j, c = c0 + ni * 16;
;         Ts[r * PITCH + c] = f2bf(vf(r, c, acc[mi][ni][j]));
;       }
; __device__ __forceinline__ void phase_moe_down(const Params& p, int l, bool last, unsigned char* smem) {
;     ...
;     auto epi = [&](f32x4(&acc)[4][4], int r0, int c0) {
;       auto vf = [&](int r, int, float v) { return (r < mvalid ? gate[r] : 0.f) * v; };
;       auto rp = [&](int r) -> u16* { return r < mvalid ? yb + (size_t)r * 1024 : nullptr; };
;       epi_staged_bf16<4>(acc, r0, c0, smem, vf, rp);
.LBB0_1546:
	s_or_b64 exec, exec, s[0:1]
	s_waitcnt lgkmcnt(0)
	v_mul_f32_e32 v53, v54, v53
	v_cvt_pk_bf16_f32 v53, v53, s0
	ds_write_b16 v65, v53 offset:96
	s_and_saveexec_b64 s[0:1], s[42:43]
	s_cbranch_execz .LBB0_1548
	v_lshl_add_u64 v[52:53], v[2:3], 2, v[162:163]
	v_mov_b32_e32 v52, v207
.LBB0_1548:
	s_or_b64 exec, exec, s[0:1]
	s_waitcnt lgkmcnt(0)
	v_mul_f32_e32 v52, v55, v52
	v_cvt_pk_bf16_f32 v52, v52, s0
	v_or_b32_e32 v53, 16, v2
	ds_write_b16 v60, v52 offset:96
	v_cmp_gt_i32_e32 vcc, s60, v53
	v_mov_b32_e32 v52, 0
	v_mov_b32_e32 v54, 0
	s_and_saveexec_b64 s[0:1], vcc
	s_cbranch_execz .LBB0_1550
	v_lshl_add_u64 v[54:55], v[2:3], 2, v[162:163]
	v_mov_b32_e32 v54, v208
.LBB0_1550:
	s_or_b64 exec, exec, s[0:1]
	s_waitcnt lgkmcnt(0)
	v_mul_f32_e32 v48, v48, v54
	v_mul_lo_u32 v53, v53, s23
	v_cvt_pk_bf16_f32 v54, v48, s0
	v_lshl_add_u32 v48, v68, 1, v53
	ds_write_b16 v48, v54
	v_or_b32_e32 v54, 17, v2
	v_cmp_gt_i32_e64 s[38:39], s60, v54
	s_and_saveexec_b64 s[0:1], s[38:39]
	s_cbranch_execz .LBB0_1552
	v_lshl_add_u64 v[54:55], v[2:3], 2, v[162:163]
	v_mov_b32_e32 v52, v209
.LBB0_1552:
	s_or_b64 exec, exec, s[0:1]
	s_waitcnt lgkmcnt(0)
	v_mul_f32_e32 v49, v49, v52
	v_add_u32_e32 v53, 0x110, v53
	v_cvt_pk_bf16_f32 v52, v49, s0
	v_lshl_add_u32 v49, v68, 1, v53
	ds_write_b16 v49, v52
	v_or_b32_e32 v52, 18, v2
	v_cmp_gt_i32_e64 s[40:41], s60, v52
	v_mov_b32_e32 v52, 0
	v_mov_b32_e32 v54, 0
	s_and_saveexec_b64 s[0:1], s[40:41]
	s_cbranch_execz .LBB0_1554
	v_lshl_add_u64 v[54:55], v[2:3], 2, v[162:163]
	v_mov_b32_e32 v54, v210
.LBB0_1554:
	s_or_b64 exec, exec, s[0:1]
	s_waitcnt lgkmcnt(0)
	v_mul_f32_e32 v50, v50, v54
	v_cvt_pk_bf16_f32 v54, v50, s0
	v_add_u32_e32 v50, 0x110, v53
	v_or_b32_e32 v53, 19, v2
	v_lshl_add_u32 v50, v68, 1, v50
	v_cmp_gt_i32_e64 s[42:43], s60, v53
	ds_write_b16 v50, v54
	s_and_saveexec_b64 s[0:1], s[42:43]
	s_cbranch_execz .LBB0_1556
	v_lshl_add_u64 v[52:53], v[2:3], 2, v[162:163]
	v_mov_b32_e32 v52, v211
.LBB0_1556:
	s_or_b64 exec, exec, s[0:1]
	s_waitcnt lgkmcnt(0)
	v_mul_f32_e32 v51, v51, v52
	v_cvt_pk_bf16_f32 v51, v51, s0
	ds_write_b16 v50, v51 offset:272
	v_mov_b32_e32 v51, 0
	v_mov_b32_e32 v52, 0
	s_and_saveexec_b64 s[0:1], vcc
	s_cbranch_execz .LBB0_1558
	v_lshl_add_u64 v[52:53], v[2:3], 2, v[162:163]
	v_mov_b32_e32 v52, v208
.LBB0_1558:
	s_or_b64 exec, exec, s[0:1]
	s_waitcnt lgkmcnt(0)
	v_mul_f32_e32 v44, v44, v52
	v_cvt_pk_bf16_f32 v44, v44, s0
	ds_write_b16 v48, v44 offset:32
	s_and_saveexec_b64 s[0:1], s[38:39]
	s_cbranch_execz .LBB0_1560
	v_lshl_add_u64 v[52:53], v[2:3], 2, v[162:163]
	v_mov_b32_e32 v51, v209
.LBB0_1560:
	s_or_b64 exec, exec, s[0:1]
	s_waitcnt lgkmcnt(0)
	v_mul_f32_e32 v44, v45, v51
	v_cvt_pk_bf16_f32 v44, v44, s0
	ds_write_b16 v49, v44 offset:32
	v_mov_b32_e32 v45, 0
	v_mov_b32_e32 v44, 0
	s_and_saveexec_b64 s[0:1], s[40:41]
	s_cbranch_execz .LBB0_1562
	v_lshl_add_u64 v[52:53], v[2:3], 2, v[162:163]
	v_mov_b32_e32 v44, v210
.LBB0_1562:
	s_or_b64 exec, exec, s[0:1]
	s_waitcnt lgkmcnt(0)
	v_mul_f32_e32 v44, v46, v44
	v_cvt_pk_bf16_f32 v44, v44, s0
	ds_write_b16 v50, v44 offset:32
	s_and_saveexec_b64 s[0:1], s[42:43]
	s_cbranch_execz .LBB0_1564
	v_lshl_add_u64 v[44:45], v[2:3], 2, v[162:163]
	v_mov_b32_e32 v45, v211
.LBB0_1564:
	s_or_b64 exec, exec, s[0:1]
	s_waitcnt lgkmcnt(0)
	v_mul_f32_e32 v45, v47, v45
	v_add_u32_e32 v44, 0x110, v50
	v_cvt_pk_bf16_f32 v45, v45, s0
	ds_write_b16 v44, v45 offset:32
	v_mov_b32_e32 v45, 0
	v_mov_b32_e32 v46, 0
	s_and_saveexec_b64 s[0:1], vcc
	s_cbranch_execz .LBB0_1566
	v_lshl_add_u64 v[46:47], v[2:3], 2, v[162:163]
	v_mov_b32_e32 v46, v208
.LBB0_1566:
	s_or_b64 exec, exec, s[0:1]
	s_waitcnt lgkmcnt(0)
	v_mul_f32_e32 v40, v40, v46
	v_cvt_pk_bf16_f32 v40, v40, s0
	ds_write_b16 v48, v40 offset:64
	s_and_saveexec_b64 s[0:1], s[38:39]
	s_cbranch_execz .LBB0_1568
	v_lshl_add_u64 v[46:47], v[2:3], 2, v[162:163]
	v_mov_b32_e32 v45, v209
.LBB0_1568:
	s_or_b64 exec, exec, s[0:1]
	s_waitcnt lgkmcnt(0)
	v_mul_f32_e32 v40, v41, v45
	v_cvt_pk_bf16_f32 v40, v40, s0
	ds_write_b16 v49, v40 offset:64
	v_mov_b32_e32 v40, 0
	v_mov_b32_e32 v41, 0
	s_and_saveexec_b64 s[0:1], s[40:41]
	s_cbranch_execz .LBB0_1570
	v_lshl_add_u64 v[46:47], v[2:3], 2, v[162:163]
	v_mov_b32_e32 v41, v210
.LBB0_1570:
	s_or_b64 exec, exec, s[0:1]
	s_waitcnt lgkmcnt(0)
	v_mul_f32_e32 v41, v42, v41
	v_cvt_pk_bf16_f32 v41, v41, s0
	ds_write_b16 v50, v41 offset:64
	s_and_saveexec_b64 s[0:1], s[42:43]
	s_cbranch_execz .LBB0_1572
	v_lshl_add_u64 v[40:41], v[2:3], 2, v[162:163]
	v_mov_b32_e32 v40, v211
.LBB0_1572:
	s_or_b64 exec, exec, s[0:1]
	s_waitcnt lgkmcnt(0)
	v_mul_f32_e32 v40, v43, v40
	v_cvt_pk_bf16_f32 v40, v40, s0
	ds_write_b16 v44, v40 offset:64
	v_mov_b32_e32 v40, 0
	v_mov_b32_e32 v41, 0
	s_and_saveexec_b64 s[0:1], vcc
	s_cbranch_execz .LBB0_1574
	v_lshl_add_u64 v[42:43], v[2:3], 2, v[162:163]
	v_mov_b32_e32 v41, v208
.LBB0_1574:
	s_or_b64 exec, exec, s[0:1]
	s_waitcnt lgkmcnt(0)
	v_mul_f32_e32 v36, v36, v41
	v_cvt_pk_bf16_f32 v36, v36, s0
	ds_write_b16 v48, v36 offset:96
	s_and_saveexec_b64 s[0:1], s[38:39]
	s_cbranch_execz .LBB0_1576
	v_lshl_add_u64 v[40:41], v[2:3], 2, v[162:163]
	v_mov_b32_e32 v40, v209
.LBB0_1576:
	s_or_b64 exec, exec, s[0:1]
	s_waitcnt lgkmcnt(0)
	v_mul_f32_e32 v36, v37, v40
	v_cvt_pk_bf16_f32 v36, v36, s0
	ds_write_b16 v49, v36 offset:96
	v_mov_b32_e32 v36, 0
	v_mov_b32_e32 v37, 0
	s_and_saveexec_b64 s[0:1], s[40:41]
	s_cbranch_execz .LBB0_1578
	v_lshl_add_u64 v[40:41], v[2:3], 2, v[162:163]
	v_mov_b32_e32 v37, v210
.LBB0_1578:
	s_or_b64 exec, exec, s[0:1]
	s_waitcnt lgkmcnt(0)
	v_mul_f32_e32 v37, v38, v37
	v_cvt_pk_bf16_f32 v37, v37, s0
	ds_write_b16 v50, v37 offset:96
	s_and_saveexec_b64 s[0:1], s[42:43]
	s_cbranch_execz .LBB0_1580
	v_lshl_add_u64 v[36:37], v[2:3], 2, v[162:163]
	v_mov_b32_e32 v36, v211
; __device__ __forceinline__ u16 f2bf(float f) { return (u16)(pack2(f, 0.f) & 0xffffu); }
; template <int NT, class VF, class RP>
; __device__ __forceinline__ void epi_staged_bf16(f32x4 (&acc)[4][NT], int r0, int c0, unsigned char* smem, VF vf, RP rowptr) {
;     ...
; #pragma unroll
;   for (int mi = 0; mi < 4; ++mi)
; #pragma unroll
;     for (int ni = 0; ni < NT; ++ni)
; #pragma unroll
;       for (int j = 0; j < 4; ++j) {
;         const int r = r0 + mi * 16 + j, c = c0 + ni * 16;
;         Ts[r * PITCH + c] = f2bf(vf(r, c, acc[mi][ni][j]));
;       }
; __device__ __forceinline__ void phase_moe_down(const Params& p, int l, bool last, unsigned char* smem) {
;     ...
;     auto epi = [&](f32x4(&acc)[4][4], int r0, int c0) {
;       auto vf = [&](int r, int, float v) { return (r < mvalid ? gate[r] : 0.f) * v; };
;       auto rp = [&](int r) -> u16* { return r < mvalid ? yb + (size_t)r * 1024 : nullptr; };
;       epi_staged_bf16<4>(acc, r0, c0, smem, vf, rp);
.LBB0_1580:
	s_or_b64 exec, exec, s[0:1]
	s_waitcnt lgkmcnt(0)
	v_mul_f32_e32 v36, v39, v36
	v_cvt_pk_bf16_f32 v36, v36, s0
	v_or_b32_e32 v37, 32, v2
	ds_write_b16 v44, v36 offset:96
	v_cmp_gt_i32_e32 vcc, s60, v37
	v_mov_b32_e32 v36, 0
	v_mov_b32_e32 v38, 0
	s_and_saveexec_b64 s[0:1], vcc
	s_cbranch_execz .LBB0_1582
	v_lshl_add_u64 v[38:39], v[2:3], 2, v[162:163]
	v_mov_b32_e32 v38, v216
.LBB0_1582:
	s_or_b64 exec, exec, s[0:1]
	s_waitcnt lgkmcnt(0)
	v_mul_f32_e32 v32, v32, v38
	v_mul_lo_u32 v37, v37, s23
	v_cvt_pk_bf16_f32 v38, v32, s0
	v_lshl_add_u32 v32, v68, 1, v37
	ds_write_b16 v32, v38
	v_or_b32_e32 v38, 33, v2
	v_cmp_gt_i32_e64 s[38:39], s60, v38
	s_and_saveexec_b64 s[0:1], s[38:39]
	s_cbranch_execz .LBB0_1584
	v_lshl_add_u64 v[38:39], v[2:3], 2, v[162:163]
	v_mov_b32_e32 v36, v217
.LBB0_1584:
	s_or_b64 exec, exec, s[0:1]
	s_waitcnt lgkmcnt(0)
	v_mul_f32_e32 v33, v33, v36
	v_add_u32_e32 v37, 0x110, v37
	v_cvt_pk_bf16_f32 v36, v33, s0
	v_lshl_add_u32 v33, v68, 1, v37
	ds_write_b16 v33, v36
	v_or_b32_e32 v36, 34, v2
	v_cmp_gt_i32_e64 s[40:41], s60, v36
	v_mov_b32_e32 v36, 0
	v_mov_b32_e32 v38, 0
	s_and_saveexec_b64 s[0:1], s[40:41]
	s_cbranch_execz .LBB0_1586
	v_lshl_add_u64 v[38:39], v[2:3], 2, v[162:163]
	v_mov_b32_e32 v38, v218
.LBB0_1586:
	s_or_b64 exec, exec, s[0:1]
	s_waitcnt lgkmcnt(0)
	v_mul_f32_e32 v34, v34, v38
	v_cvt_pk_bf16_f32 v38, v34, s0
	v_add_u32_e32 v34, 0x110, v37
	v_or_b32_e32 v37, 35, v2
	v_lshl_add_u32 v34, v68, 1, v34
	v_cmp_gt_i32_e64 s[42:43], s60, v37
	ds_write_b16 v34, v38
	s_and_saveexec_b64 s[0:1], s[42:43]
	s_cbranch_execz .LBB0_1588
	v_lshl_add_u64 v[36:37], v[2:3], 2, v[162:163]
	v_mov_b32_e32 v36, v219
.LBB0_1588:
	s_or_b64 exec, exec, s[0:1]
	s_waitcnt lgkmcnt(0)
	v_mul_f32_e32 v35, v35, v36
	v_cvt_pk_bf16_f32 v35, v35, s0
	ds_write_b16 v34, v35 offset:272
	v_mov_b32_e32 v35, 0
	v_mov_b32_e32 v36, 0
	s_and_saveexec_b64 s[0:1], vcc
	s_cbranch_execz .LBB0_1590
	v_lshl_add_u64 v[36:37], v[2:3], 2, v[162:163]
	v_mov_b32_e32 v36, v216
.LBB0_1590:
	s_or_b64 exec, exec, s[0:1]
	s_waitcnt lgkmcnt(0)
	v_mul_f32_e32 v28, v28, v36
	v_cvt_pk_bf16_f32 v28, v28, s0
	ds_write_b16 v32, v28 offset:32
	s_and_saveexec_b64 s[0:1], s[38:39]
	s_cbranch_execz .LBB0_1592
	v_lshl_add_u64 v[36:37], v[2:3], 2, v[162:163]
	v_mov_b32_e32 v35, v217
.LBB0_1592:
	s_or_b64 exec, exec, s[0:1]
	s_waitcnt lgkmcnt(0)
	v_mul_f32_e32 v28, v29, v35
	v_cvt_pk_bf16_f32 v28, v28, s0
	ds_write_b16 v33, v28 offset:32
	v_mov_b32_e32 v29, 0
	v_mov_b32_e32 v28, 0
	s_and_saveexec_b64 s[0:1], s[40:41]
	s_cbranch_execz .LBB0_1594
	v_lshl_add_u64 v[36:37], v[2:3], 2, v[162:163]
	v_mov_b32_e32 v28, v218
.LBB0_1594:
	s_or_b64 exec, exec, s[0:1]
	s_waitcnt lgkmcnt(0)
	v_mul_f32_e32 v28, v30, v28
	v_cvt_pk_bf16_f32 v28, v28, s0
	ds_write_b16 v34, v28 offset:32
	s_and_saveexec_b64 s[0:1], s[42:43]
	s_cbranch_execz .LBB0_1596
	v_lshl_add_u64 v[28:29], v[2:3], 2, v[162:163]
	v_mov_b32_e32 v29, v219
.LBB0_1596:
	s_or_b64 exec, exec, s[0:1]
	s_waitcnt lgkmcnt(0)
	v_mul_f32_e32 v29, v31, v29
	v_add_u32_e32 v28, 0x110, v34
	v_cvt_pk_bf16_f32 v29, v29, s0
	ds_write_b16 v28, v29 offset:32
	v_mov_b32_e32 v29, 0
	v_mov_b32_e32 v30, 0
	s_and_saveexec_b64 s[0:1], vcc
	s_cbranch_execz .LBB0_1598
	v_lshl_add_u64 v[30:31], v[2:3], 2, v[162:163]
	v_mov_b32_e32 v30, v216
.LBB0_1598:
	s_or_b64 exec, exec, s[0:1]
	s_waitcnt lgkmcnt(0)
	v_mul_f32_e32 v24, v24, v30
	v_cvt_pk_bf16_f32 v24, v24, s0
	ds_write_b16 v32, v24 offset:64
	s_and_saveexec_b64 s[0:1], s[38:39]
	s_cbranch_execz .LBB0_1600
	v_lshl_add_u64 v[30:31], v[2:3], 2, v[162:163]
	v_mov_b32_e32 v29, v217
.LBB0_1600:
	s_or_b64 exec, exec, s[0:1]
	s_waitcnt lgkmcnt(0)
	v_mul_f32_e32 v24, v25, v29
	v_cvt_pk_bf16_f32 v24, v24, s0
	ds_write_b16 v33, v24 offset:64
	v_mov_b32_e32 v24, 0
	v_mov_b32_e32 v25, 0
	s_and_saveexec_b64 s[0:1], s[40:41]
	s_cbranch_execz .LBB0_1602
	v_lshl_add_u64 v[30:31], v[2:3], 2, v[162:163]
	v_mov_b32_e32 v25, v218
.LBB0_1602:
	s_or_b64 exec, exec, s[0:1]
	s_waitcnt lgkmcnt(0)
	v_mul_f32_e32 v25, v26, v25
	v_cvt_pk_bf16_f32 v25, v25, s0
	ds_write_b16 v34, v25 offset:64
	s_and_saveexec_b64 s[0:1], s[42:43]
	s_cbranch_execz .LBB0_1604
	v_lshl_add_u64 v[24:25], v[2:3], 2, v[162:163]
	v_mov_b32_e32 v24, v219
.LBB0_1604:
	s_or_b64 exec, exec, s[0:1]
	s_waitcnt lgkmcnt(0)
	v_mul_f32_e32 v24, v27, v24
	v_cvt_pk_bf16_f32 v24, v24, s0
	ds_write_b16 v28, v24 offset:64
	v_mov_b32_e32 v24, 0
	v_mov_b32_e32 v25, 0
	s_and_saveexec_b64 s[0:1], vcc
	s_cbranch_execz .LBB0_1606
	v_lshl_add_u64 v[26:27], v[2:3], 2, v[162:163]
	v_mov_b32_e32 v25, v216
.LBB0_1606:
	s_or_b64 exec, exec, s[0:1]
	s_waitcnt lgkmcnt(0)
	v_mul_f32_e32 v20, v20, v25
	v_cvt_pk_bf16_f32 v20, v20, s0
	ds_write_b16 v32, v20 offset:96
	s_and_saveexec_b64 s[0:1], s[38:39]
	s_cbranch_execz .LBB0_1608
	v_lshl_add_u64 v[24:25], v[2:3], 2, v[162:163]
	v_mov_b32_e32 v24, v217
.LBB0_1608:
	s_or_b64 exec, exec, s[0:1]
	s_waitcnt lgkmcnt(0)
	v_mul_f32_e32 v20, v21, v24
	v_cvt_pk_bf16_f32 v20, v20, s0
	ds_write_b16 v33, v20 offset:96
	v_mov_b32_e32 v20, 0
	v_mov_b32_e32 v21, 0
	s_and_saveexec_b64 s[0:1], s[40:41]
	s_cbranch_execz .LBB0_1610
	v_lshl_add_u64 v[24:25], v[2:3], 2, v[162:163]
	v_mov_b32_e32 v21, v218
.LBB0_1610:
	s_or_b64 exec, exec, s[0:1]
	s_waitcnt lgkmcnt(0)
	v_mul_f32_e32 v21, v22, v21
	v_cvt_pk_bf16_f32 v21, v21, s0
	ds_write_b16 v34, v21 offset:96
	s_and_saveexec_b64 s[0:1], s[42:43]
	s_cbranch_execz .LBB0_1612
	v_lshl_add_u64 v[20:21], v[2:3], 2, v[162:163]
	v_mov_b32_e32 v20, v219
; __device__ __forceinline__ u16 f2bf(float f) { return (u16)(pack2(f, 0.f) & 0xffffu); }
; template <int NT, class VF, class RP>
; __device__ __forceinline__ void epi_staged_bf16(f32x4 (&acc)[4][NT], int r0, int c0, unsigned char* smem, VF vf, RP rowptr) {
;     ...
; #pragma unroll
;   for (int mi = 0; mi < 4; ++mi)
; #pragma unroll
;     for (int ni = 0; ni < NT; ++ni)
; #pragma unroll
;       for (int j = 0; j < 4; ++j) {
;         const int r = r0 + mi * 16 + j, c = c0 + ni * 16;
;         Ts[r * PITCH + c] = f2bf(vf(r, c, acc[mi][ni][j]));
;       }
;   __syncthreads();
; #pragma unroll
;   for (int i = 0; i < CPR / 2; ++i) {
;     const int c = t + 256 * i, row = c / CPR, ch = c % CPR;
;     u16* d = rowptr(row);
;     if (d) *(u32x4*)(d + ch * 8) = *(const u32x4*)(Ts + row * PITCH + ch * 8);
;   }
; __device__ __forceinline__ void phase_moe_down(const Params& p, int l, bool last, unsigned char* smem) {
;     ...
;     auto epi = [&](f32x4(&acc)[4][4], int r0, int c0) {
;       auto vf = [&](int r, int, float v) { return (r < mvalid ? gate[r] : 0.f) * v; };
;       auto rp = [&](int r) -> u16* { return r < mvalid ? yb + (size_t)r * 1024 : nullptr; };
;       epi_staged_bf16<4>(acc, r0, c0, smem, vf, rp);
.LBB0_1612:
	s_or_b64 exec, exec, s[0:1]
	s_waitcnt lgkmcnt(0)
	v_mul_f32_e32 v20, v23, v20
	v_cvt_pk_bf16_f32 v20, v20, s0
	v_or_b32_e32 v21, 48, v2
	ds_write_b16 v28, v20 offset:96
	v_cmp_gt_i32_e32 vcc, s60, v21
	v_mov_b32_e32 v20, 0
	v_mov_b32_e32 v22, 0
	s_and_saveexec_b64 s[0:1], vcc
	s_cbranch_execz .LBB0_1614
	v_lshl_add_u64 v[22:23], v[2:3], 2, v[162:163]
	v_mov_b32_e32 v22, v220
.LBB0_1614:
	s_or_b64 exec, exec, s[0:1]
	s_waitcnt lgkmcnt(0)
	v_mul_f32_e32 v16, v16, v22
	v_mul_lo_u32 v21, v21, s23
	v_cvt_pk_bf16_f32 v22, v16, s0
	v_lshl_add_u32 v16, v68, 1, v21
	ds_write_b16 v16, v22
	v_or_b32_e32 v22, 49, v2
	v_cmp_gt_i32_e64 s[38:39], s60, v22
	s_and_saveexec_b64 s[0:1], s[38:39]
	s_cbranch_execz .LBB0_1616
	v_lshl_add_u64 v[22:23], v[2:3], 2, v[162:163]
	v_mov_b32_e32 v20, v221
.LBB0_1616:
	s_or_b64 exec, exec, s[0:1]
	s_waitcnt lgkmcnt(0)
	v_mul_f32_e32 v17, v17, v20
	v_add_u32_e32 v21, 0x110, v21
	v_cvt_pk_bf16_f32 v20, v17, s0
	v_lshl_add_u32 v17, v68, 1, v21
	ds_write_b16 v17, v20
	v_or_b32_e32 v20, 50, v2
	v_cmp_gt_i32_e64 s[40:41], s60, v20
	v_mov_b32_e32 v20, 0
	v_mov_b32_e32 v22, 0
	s_and_saveexec_b64 s[0:1], s[40:41]
	s_cbranch_execz .LBB0_1618
	v_lshl_add_u64 v[22:23], v[2:3], 2, v[162:163]
	v_mov_b32_e32 v22, v222
.LBB0_1618:
	s_or_b64 exec, exec, s[0:1]
	s_waitcnt lgkmcnt(0)
	v_mul_f32_e32 v18, v18, v22
	v_cvt_pk_bf16_f32 v22, v18, s0
	v_add_u32_e32 v18, 0x110, v21
	v_or_b32_e32 v21, 51, v2
	v_lshl_add_u32 v18, v68, 1, v18
	v_cmp_gt_i32_e64 s[42:43], s60, v21
	ds_write_b16 v18, v22
	s_and_saveexec_b64 s[0:1], s[42:43]
	s_cbranch_execz .LBB0_1620
	v_lshl_add_u64 v[20:21], v[2:3], 2, v[162:163]
	v_mov_b32_e32 v20, v223
.LBB0_1620:
	s_or_b64 exec, exec, s[0:1]
	s_waitcnt lgkmcnt(0)
	v_mul_f32_e32 v19, v19, v20
	v_cvt_pk_bf16_f32 v19, v19, s0
	ds_write_b16 v18, v19 offset:272
	v_mov_b32_e32 v19, 0
	v_mov_b32_e32 v20, 0
	s_and_saveexec_b64 s[0:1], vcc
	s_cbranch_execz .LBB0_1622
	v_lshl_add_u64 v[20:21], v[2:3], 2, v[162:163]
	v_mov_b32_e32 v20, v220
.LBB0_1622:
	s_or_b64 exec, exec, s[0:1]
	s_waitcnt lgkmcnt(0)
	v_mul_f32_e32 v12, v12, v20
	v_cvt_pk_bf16_f32 v12, v12, s0
	ds_write_b16 v16, v12 offset:32
	s_and_saveexec_b64 s[0:1], s[38:39]
	s_cbranch_execz .LBB0_1624
	v_lshl_add_u64 v[20:21], v[2:3], 2, v[162:163]
	v_mov_b32_e32 v19, v221
.LBB0_1624:
	s_or_b64 exec, exec, s[0:1]
	s_waitcnt lgkmcnt(0)
	v_mul_f32_e32 v12, v13, v19
	v_cvt_pk_bf16_f32 v12, v12, s0
	ds_write_b16 v17, v12 offset:32
	v_mov_b32_e32 v13, 0
	v_mov_b32_e32 v12, 0
	s_and_saveexec_b64 s[0:1], s[40:41]
	s_cbranch_execz .LBB0_1626
	v_lshl_add_u64 v[20:21], v[2:3], 2, v[162:163]
	v_mov_b32_e32 v12, v222
.LBB0_1626:
	s_or_b64 exec, exec, s[0:1]
	s_waitcnt lgkmcnt(0)
	v_mul_f32_e32 v12, v14, v12
	v_cvt_pk_bf16_f32 v12, v12, s0
	ds_write_b16 v18, v12 offset:32
	s_and_saveexec_b64 s[0:1], s[42:43]
	s_cbranch_execz .LBB0_1628
	v_lshl_add_u64 v[12:13], v[2:3], 2, v[162:163]
	v_mov_b32_e32 v13, v223
.LBB0_1628:
	s_or_b64 exec, exec, s[0:1]
	s_waitcnt lgkmcnt(0)
	v_mul_f32_e32 v13, v15, v13
	v_add_u32_e32 v12, 0x110, v18
	v_cvt_pk_bf16_f32 v13, v13, s0
	ds_write_b16 v12, v13 offset:32
	v_mov_b32_e32 v13, 0
	v_mov_b32_e32 v14, 0
	s_and_saveexec_b64 s[0:1], vcc
	s_cbranch_execz .LBB0_1630
	v_lshl_add_u64 v[14:15], v[2:3], 2, v[162:163]
	v_mov_b32_e32 v14, v220
.LBB0_1630:
	s_or_b64 exec, exec, s[0:1]
	s_waitcnt lgkmcnt(0)
	v_mul_f32_e32 v8, v8, v14
	v_cvt_pk_bf16_f32 v8, v8, s0
	ds_write_b16 v16, v8 offset:64
	s_and_saveexec_b64 s[0:1], s[38:39]
	s_cbranch_execz .LBB0_1632
	v_lshl_add_u64 v[14:15], v[2:3], 2, v[162:163]
	v_mov_b32_e32 v13, v221
.LBB0_1632:
	s_or_b64 exec, exec, s[0:1]
	s_waitcnt lgkmcnt(0)
	v_mul_f32_e32 v8, v9, v13
	v_cvt_pk_bf16_f32 v8, v8, s0
	ds_write_b16 v17, v8 offset:64
	v_mov_b32_e32 v8, 0
	v_mov_b32_e32 v9, 0
	s_and_saveexec_b64 s[0:1], s[40:41]
	s_cbranch_execz .LBB0_1634
	v_lshl_add_u64 v[14:15], v[2:3], 2, v[162:163]
	v_mov_b32_e32 v9, v222
.LBB0_1634:
	s_or_b64 exec, exec, s[0:1]
	s_waitcnt lgkmcnt(0)
	v_mul_f32_e32 v9, v10, v9
	v_cvt_pk_bf16_f32 v9, v9, s0
	ds_write_b16 v18, v9 offset:64
	s_and_saveexec_b64 s[0:1], s[42:43]
	s_cbranch_execz .LBB0_1636
	v_lshl_add_u64 v[8:9], v[2:3], 2, v[162:163]
	v_mov_b32_e32 v8, v223
.LBB0_1636:
	s_or_b64 exec, exec, s[0:1]
	s_waitcnt lgkmcnt(0)
	v_mul_f32_e32 v8, v11, v8
	v_cvt_pk_bf16_f32 v8, v8, s0
	ds_write_b16 v12, v8 offset:64
	v_mov_b32_e32 v8, 0
	v_mov_b32_e32 v9, 0
	s_and_saveexec_b64 s[0:1], vcc
	s_cbranch_execz .LBB0_1638
	v_lshl_add_u64 v[10:11], v[2:3], 2, v[162:163]
	v_mov_b32_e32 v9, v220
.LBB0_1638:
	s_or_b64 exec, exec, s[0:1]
	s_waitcnt lgkmcnt(0)
	v_mul_f32_e32 v4, v4, v9
	v_cvt_pk_bf16_f32 v4, v4, s0
	ds_write_b16 v16, v4 offset:96
	s_and_saveexec_b64 s[0:1], s[38:39]
	s_cbranch_execz .LBB0_1640
	v_lshl_add_u64 v[8:9], v[2:3], 2, v[162:163]
	v_mov_b32_e32 v8, v221
.LBB0_1640:
	s_or_b64 exec, exec, s[0:1]
	s_waitcnt lgkmcnt(0)
	v_mul_f32_e32 v4, v5, v8
	v_cvt_pk_bf16_f32 v4, v4, s0
	ds_write_b16 v17, v4 offset:96
	v_mov_b32_e32 v4, 0
	v_mov_b32_e32 v5, 0
	s_and_saveexec_b64 s[0:1], s[40:41]
	s_cbranch_execz .LBB0_1642
	v_lshl_add_u64 v[8:9], v[2:3], 2, v[162:163]
	v_mov_b32_e32 v5, v222
.LBB0_1642:
	s_or_b64 exec, exec, s[0:1]
	s_waitcnt lgkmcnt(0)
	v_mul_f32_e32 v5, v6, v5
	v_cvt_pk_bf16_f32 v5, v5, s0
	ds_write_b16 v18, v5 offset:96
	s_and_saveexec_b64 s[0:1], s[42:43]
	s_cbranch_execz .LBB0_1644
	v_lshl_add_u64 v[2:3], v[2:3], 2, v[162:163]
	v_mov_b32_e32 v4, v223
.LBB0_1644:
	s_or_b64 exec, exec, s[0:1]
	s_waitcnt lgkmcnt(0)
	v_mul_f32_e32 v2, v7, v4
	v_cvt_pk_bf16_f32 v2, v2, s0
	ds_write_b16 v12, v2 offset:96
	v_ashrrev_i32_e32 v2, 31, v0
	v_lshrrev_b32_e32 v2, 28, v2
	v_add_u32_e32 v2, v0, v2
	v_ashrrev_i32_e32 v2, 4, v2
	v_cmp_gt_i32_e64 s[38:39], s60, v2
	v_cmp_ne_u64_e64 s[40:41], 0, v[164:165]
	v_cmp_eq_u64_e32 vcc, 0, v[164:165]
	s_and_b64 s[8:9], s[38:39], s[40:41]
	s_waitcnt lgkmcnt(0)
	s_barrier
	s_and_saveexec_b64 s[0:1], s[8:9]
	s_cbranch_execz .LBB0_1646
	v_ashrrev_i32_e32 v3, 31, v2
	v_lshlrev_b64 v[6:7], 11, v[2:3]
	v_lshlrev_b32_e32 v3, 4, v2
	v_sub_u32_e32 v8, v0, v3
	v_mul_lo_u32 v2, v2, s23
	v_lshl_add_u32 v2, v8, 4, v2
	ds_read_b128 v[2:5], v2
	v_lshlrev_b32_e32 v8, 3, v8
	v_lshl_add_u64 v[6:7], v[160:161], 0, v[6:7]
	v_ashrrev_i32_e32 v9, 31, v8
	v_lshl_add_u64 v[6:7], v[8:9], 1, v[6:7]
	s_waitcnt lgkmcnt(0)
	global_store_dwordx4 v[6:7], v[2:5], off
